# K-loops: s_sleep 2 at start of each load segment (stagger vs MFMA partner) + SwiGLU loop LDS-DMA saddr form (no VALU 64-bit adds)
# baseline (speedup 1.0000x reference)
.LBB0_147:
	s_sleep 2
	s_add_u32 s42, s40, 0xfff80080
	s_addc_u32 s43, s41, -1
	s_add_i32 s71, 0, 0x10000
	s_cmp_eq_u32 s63, 28
	s_cselect_b32 s45, s2, s43
	s_cselect_b32 s44, s5, s42
	s_cselect_b32 s43, s23, s62
	s_cselect_b32 s42, s25, s31
	s_add_i32 s73, 0, 0x14000
	s_waitcnt lgkmcnt(0)
	v_add_u32_e32 v156, s71, v169
	v_add_u32_e32 v178, s73, v169
	ds_read_b128 v[132:135], v156
	ds_read_b128 v[136:139], v156 offset:1024
	ds_read_b128 v[152:155], v156 offset:2048
	ds_read_b128 v[156:159], v156 offset:3072
	ds_read_b128 v[160:163], v178
	ds_read_b128 v[164:167], v178 offset:1024
	ds_read_b128 v[174:177], v178 offset:2048
	ds_read_b128 v[178:181], v178 offset:3072
	v_lshl_add_u64 v[202:203], s[40:41], 0, v[148:149]
	s_add_i32 m0, s53, 0xc000
	ds_read_b128 v[182:185], v171
	ds_read_b128 v[186:189], v171 offset:1024
	ds_read_b128 v[190:193], v171 offset:2048
	ds_read_b128 v[194:197], v171 offset:3072
	ds_read_b128 v[198:201], v171 offset:4096
	ds_read_b128 v[208:211], v171 offset:5120
	ds_read_b128 v[212:215], v171 offset:6144
	ds_read_b128 v[216:219], v171 offset:7168
	global_load_lds_dwordx4 v[202:203], off
	v_lshl_add_u64 v[202:203], s[40:41], 0, v[150:151]
	s_add_i32 m0, s53, 0xe000
	s_nop 0
	global_load_lds_dwordx4 v[202:203], off
	s_waitcnt vmcnt(8)
	s_waitcnt lgkmcnt(0)
	s_barrier
	s_setprio 1
	s_waitcnt lgkmcnt(0)
	v_mfma_f32_16x16x32_bf16 v[128:131], v[132:135], v[182:185], v[128:131]
	v_mfma_f32_16x16x32_bf16 v[124:127], v[152:155], v[182:185], v[124:127]
	v_mfma_f32_16x16x32_bf16 v[120:123], v[132:135], v[190:193], v[120:123]
	v_mfma_f32_16x16x32_bf16 v[112:115], v[152:155], v[190:193], v[112:115]
	v_mfma_f32_16x16x32_bf16 v[104:107], v[132:135], v[198:201], v[104:107]
	v_mfma_f32_16x16x32_bf16 v[96:99], v[152:155], v[198:201], v[96:99]
	v_mfma_f32_16x16x32_bf16 v[88:91], v[132:135], v[212:215], v[88:91]
	v_mfma_f32_16x16x32_bf16 v[80:83], v[152:155], v[212:215], v[80:83]
	v_mfma_f32_16x16x32_bf16 v[128:131], v[136:139], v[186:189], v[128:131]
	v_mfma_f32_16x16x32_bf16 v[124:127], v[156:159], v[186:189], v[124:127]
	v_mfma_f32_16x16x32_bf16 v[120:123], v[136:139], v[194:197], v[120:123]
	v_mfma_f32_16x16x32_bf16 v[112:115], v[156:159], v[194:197], v[112:115]
	v_mfma_f32_16x16x32_bf16 v[104:107], v[136:139], v[208:211], v[104:107]
	v_mfma_f32_16x16x32_bf16 v[96:99], v[156:159], v[208:211], v[96:99]
	v_mfma_f32_16x16x32_bf16 v[88:91], v[136:139], v[216:219], v[88:91]
	v_mfma_f32_16x16x32_bf16 v[80:83], v[156:159], v[216:219], v[80:83]
	s_setprio 0
	s_setprio 1
	v_mfma_f32_16x16x32_bf16 v[116:119], v[160:163], v[182:185], v[116:119]
	v_mfma_f32_16x16x32_bf16 v[108:111], v[174:177], v[182:185], v[108:111]
	v_mfma_f32_16x16x32_bf16 v[100:103], v[160:163], v[190:193], v[100:103]
	v_mfma_f32_16x16x32_bf16 v[92:95], v[174:177], v[190:193], v[92:95]
	v_mfma_f32_16x16x32_bf16 v[84:87], v[160:163], v[198:201], v[84:87]
	v_mfma_f32_16x16x32_bf16 v[76:79], v[174:177], v[198:201], v[76:79]
	v_mfma_f32_16x16x32_bf16 v[72:75], v[160:163], v[212:215], v[72:75]
	v_mfma_f32_16x16x32_bf16 v[68:71], v[174:177], v[212:215], v[68:71]
	v_mfma_f32_16x16x32_bf16 v[116:119], v[164:167], v[186:189], v[116:119]
	v_mfma_f32_16x16x32_bf16 v[108:111], v[178:181], v[186:189], v[108:111]
	v_mfma_f32_16x16x32_bf16 v[100:103], v[164:167], v[194:197], v[100:103]
	v_mfma_f32_16x16x32_bf16 v[92:95], v[178:181], v[194:197], v[92:95]
	v_mfma_f32_16x16x32_bf16 v[84:87], v[164:167], v[208:211], v[84:87]
	v_mfma_f32_16x16x32_bf16 v[76:79], v[178:181], v[208:211], v[76:79]
	v_mfma_f32_16x16x32_bf16 v[72:75], v[164:167], v[216:219], v[72:75]
	v_mfma_f32_16x16x32_bf16 v[68:71], v[178:181], v[216:219], v[68:71]
	s_setprio 0
	s_barrier
	s_sleep 2
	s_add_i32 s71, s71, s51
	v_lshl_add_u64 v[202:203], s[42:43], 0, v[2:3]
	s_mov_b32 m0, s71
	ds_read_b128 v[182:185], v171 offset:16384
	ds_read_b128 v[186:189], v171 offset:17408
	ds_read_b128 v[190:193], v171 offset:18432
	ds_read_b128 v[194:197], v171 offset:19456
	ds_read_b128 v[198:201], v171 offset:20480
	ds_read_b128 v[208:211], v171 offset:21504
	ds_read_b128 v[212:215], v171 offset:22528
	ds_read_b128 v[216:219], v171 offset:23552
	global_load_lds_dwordx4 v[202:203], off
	s_add_i32 m0, s71, 0x2000
	s_add_u32 s74, s42, 0x80000
	v_lshl_add_u64 v[204:205], s[42:43], 0, v[142:143]
	s_addc_u32 s75, s43, 0
	s_add_i32 s71, s73, s51
	global_load_lds_dwordx4 v[204:205], off
	v_lshl_add_u64 v[206:207], s[74:75], 0, v[2:3]
	s_mov_b32 m0, s71
	v_lshl_add_u64 v[220:221], s[44:45], 0, v[140:141]
	global_load_lds_dwordx4 v[206:207], off
	v_lshl_add_u64 v[206:207], s[74:75], 0, v[142:143]
	s_add_i32 m0, s71, 0x2000
	s_nop 0
	global_load_lds_dwordx4 v[206:207], off
	v_lshl_add_u64 v[206:207], s[44:45], 0, v[0:1]
	s_mov_b32 m0, s53
	s_nop 0
	global_load_lds_dwordx4 v[206:207], off
	s_mov_b32 m0, s54
	s_nop 0
	global_load_lds_dwordx4 v[220:221], off
	s_waitcnt vmcnt(8)
	s_waitcnt lgkmcnt(0)
	s_barrier
	s_setprio 1
	s_waitcnt lgkmcnt(0)
	v_mfma_f32_16x16x32_bf16 v[64:67], v[132:135], v[182:185], v[64:67]
	v_mfma_f32_16x16x32_bf16 v[60:63], v[152:155], v[182:185], v[60:63]
	v_mfma_f32_16x16x32_bf16 v[56:59], v[132:135], v[190:193], v[56:59]
	v_mfma_f32_16x16x32_bf16 v[48:51], v[152:155], v[190:193], v[48:51]
	v_mfma_f32_16x16x32_bf16 v[40:43], v[132:135], v[198:201], v[40:43]
	v_mfma_f32_16x16x32_bf16 v[32:35], v[152:155], v[198:201], v[32:35]
	v_mfma_f32_16x16x32_bf16 v[24:27], v[132:135], v[212:215], v[24:27]
	v_mfma_f32_16x16x32_bf16 v[16:19], v[152:155], v[212:215], v[16:19]
	v_mfma_f32_16x16x32_bf16 v[64:67], v[136:139], v[186:189], v[64:67]
	v_mfma_f32_16x16x32_bf16 v[60:63], v[156:159], v[186:189], v[60:63]
	v_mfma_f32_16x16x32_bf16 v[56:59], v[136:139], v[194:197], v[56:59]
	v_mfma_f32_16x16x32_bf16 v[48:51], v[156:159], v[194:197], v[48:51]
	v_mfma_f32_16x16x32_bf16 v[40:43], v[136:139], v[208:211], v[40:43]
	v_mfma_f32_16x16x32_bf16 v[32:35], v[156:159], v[208:211], v[32:35]
	v_mfma_f32_16x16x32_bf16 v[24:27], v[136:139], v[216:219], v[24:27]
	v_mfma_f32_16x16x32_bf16 v[16:19], v[156:159], v[216:219], v[16:19]
	s_setprio 0
	s_setprio 1
	v_mfma_f32_16x16x32_bf16 v[52:55], v[160:163], v[182:185], v[52:55]
	v_mfma_f32_16x16x32_bf16 v[44:47], v[174:177], v[182:185], v[44:47]
	v_mfma_f32_16x16x32_bf16 v[36:39], v[160:163], v[190:193], v[36:39]
	v_mfma_f32_16x16x32_bf16 v[28:31], v[174:177], v[190:193], v[28:31]
	v_mfma_f32_16x16x32_bf16 v[20:23], v[160:163], v[198:201], v[20:23]
	v_mfma_f32_16x16x32_bf16 v[12:15], v[174:177], v[198:201], v[12:15]
	v_mfma_f32_16x16x32_bf16 v[8:11], v[160:163], v[212:215], v[8:11]
	v_mfma_f32_16x16x32_bf16 v[4:7], v[174:177], v[212:215], v[4:7]
	v_mfma_f32_16x16x32_bf16 v[52:55], v[164:167], v[186:189], v[52:55]
	v_mfma_f32_16x16x32_bf16 v[44:47], v[178:181], v[186:189], v[44:47]
	v_mfma_f32_16x16x32_bf16 v[36:39], v[164:167], v[194:197], v[36:39]
	v_mfma_f32_16x16x32_bf16 v[28:31], v[178:181], v[194:197], v[28:31]
	v_mfma_f32_16x16x32_bf16 v[20:23], v[164:167], v[208:211], v[20:23]
	v_mfma_f32_16x16x32_bf16 v[12:15], v[178:181], v[208:211], v[12:15]
	v_mfma_f32_16x16x32_bf16 v[8:11], v[164:167], v[216:219], v[8:11]
	v_mfma_f32_16x16x32_bf16 v[4:7], v[178:181], v[216:219], v[4:7]
	s_setprio 0
	s_barrier
	s_sleep 2
	s_add_i32 s71, 0, 0x18000
	s_add_i32 s73, 0, 0x1c000
	v_add_u32_e32 v156, s71, v169
	v_add_u32_e32 v178, s73, v169
	ds_read_b128 v[132:135], v156
	ds_read_b128 v[136:139], v156 offset:1024
	ds_read_b128 v[152:155], v156 offset:2048
	ds_read_b128 v[156:159], v156 offset:3072
	ds_read_b128 v[160:163], v178
	ds_read_b128 v[164:167], v178 offset:1024
	ds_read_b128 v[174:177], v178 offset:2048
	ds_read_b128 v[178:181], v178 offset:3072
	s_add_u32 s44, s44, 0x80000
	s_addc_u32 s45, s45, 0
	s_mov_b32 m0, s55
	v_lshl_add_u64 v[222:223], s[44:45], 0, v[0:1]
	ds_read_b128 v[182:185], v171 offset:32768
	ds_read_b128 v[186:189], v171 offset:33792
	ds_read_b128 v[190:193], v171 offset:34816
	ds_read_b128 v[194:197], v171 offset:35840
	ds_read_b128 v[198:201], v171 offset:36864
	ds_read_b128 v[208:211], v171 offset:37888
	ds_read_b128 v[212:215], v171 offset:38912
	ds_read_b128 v[216:219], v171 offset:39936
	global_load_lds_dwordx4 v[222:223], off
	v_lshl_add_u64 v[222:223], s[44:45], 0, v[140:141]
	s_mov_b32 m0, s56
	s_nop 0
	global_load_lds_dwordx4 v[222:223], off
	s_waitcnt vmcnt(8)
	s_waitcnt lgkmcnt(0)
	s_barrier
	s_setprio 1
	s_waitcnt lgkmcnt(0)
	v_mfma_f32_16x16x32_bf16 v[128:131], v[132:135], v[182:185], v[128:131]
	v_mfma_f32_16x16x32_bf16 v[124:127], v[152:155], v[182:185], v[124:127]
	v_mfma_f32_16x16x32_bf16 v[120:123], v[132:135], v[190:193], v[120:123]
	v_mfma_f32_16x16x32_bf16 v[112:115], v[152:155], v[190:193], v[112:115]
	v_mfma_f32_16x16x32_bf16 v[104:107], v[132:135], v[198:201], v[104:107]
	v_mfma_f32_16x16x32_bf16 v[96:99], v[152:155], v[198:201], v[96:99]
	v_mfma_f32_16x16x32_bf16 v[88:91], v[132:135], v[212:215], v[88:91]
	v_mfma_f32_16x16x32_bf16 v[80:83], v[152:155], v[212:215], v[80:83]
	v_mfma_f32_16x16x32_bf16 v[128:131], v[136:139], v[186:189], v[128:131]
	v_mfma_f32_16x16x32_bf16 v[124:127], v[156:159], v[186:189], v[124:127]
	v_mfma_f32_16x16x32_bf16 v[120:123], v[136:139], v[194:197], v[120:123]
	v_mfma_f32_16x16x32_bf16 v[112:115], v[156:159], v[194:197], v[112:115]
	v_mfma_f32_16x16x32_bf16 v[104:107], v[136:139], v[208:211], v[104:107]
	v_mfma_f32_16x16x32_bf16 v[96:99], v[156:159], v[208:211], v[96:99]
	v_mfma_f32_16x16x32_bf16 v[88:91], v[136:139], v[216:219], v[88:91]
	v_mfma_f32_16x16x32_bf16 v[80:83], v[156:159], v[216:219], v[80:83]
	s_setprio 0
	s_setprio 1
	v_mfma_f32_16x16x32_bf16 v[116:119], v[160:163], v[182:185], v[116:119]
	v_mfma_f32_16x16x32_bf16 v[108:111], v[174:177], v[182:185], v[108:111]
	v_mfma_f32_16x16x32_bf16 v[100:103], v[160:163], v[190:193], v[100:103]
	v_mfma_f32_16x16x32_bf16 v[92:95], v[174:177], v[190:193], v[92:95]
	v_mfma_f32_16x16x32_bf16 v[84:87], v[160:163], v[198:201], v[84:87]
	v_mfma_f32_16x16x32_bf16 v[76:79], v[174:177], v[198:201], v[76:79]
	v_mfma_f32_16x16x32_bf16 v[72:75], v[160:163], v[212:215], v[72:75]
	v_mfma_f32_16x16x32_bf16 v[68:71], v[174:177], v[212:215], v[68:71]
	v_mfma_f32_16x16x32_bf16 v[116:119], v[164:167], v[186:189], v[116:119]
	v_mfma_f32_16x16x32_bf16 v[108:111], v[178:181], v[186:189], v[108:111]
	v_mfma_f32_16x16x32_bf16 v[100:103], v[164:167], v[194:197], v[100:103]
	v_mfma_f32_16x16x32_bf16 v[92:95], v[178:181], v[194:197], v[92:95]
	v_mfma_f32_16x16x32_bf16 v[84:87], v[164:167], v[208:211], v[84:87]
	v_mfma_f32_16x16x32_bf16 v[76:79], v[178:181], v[208:211], v[76:79]
	v_mfma_f32_16x16x32_bf16 v[72:75], v[164:167], v[216:219], v[72:75]
	v_mfma_f32_16x16x32_bf16 v[68:71], v[178:181], v[216:219], v[68:71]
	s_setprio 0
	s_barrier
	s_sleep 2
	s_add_i32 s44, s71, s51
	v_lshl_add_u64 v[202:203], v[202:203], 0, s[66:67]
	s_mov_b32 m0, s44
	ds_read_b128 v[182:185], v171 offset:49152
	ds_read_b128 v[186:189], v171 offset:50176
	ds_read_b128 v[190:193], v171 offset:51200
	ds_read_b128 v[194:197], v171 offset:52224
	ds_read_b128 v[198:201], v171 offset:53248
	ds_read_b128 v[208:211], v171 offset:54272
	ds_read_b128 v[212:215], v171 offset:55296
	ds_read_b128 v[216:219], v171 offset:56320
	global_load_lds_dwordx4 v[202:203], off
	s_add_i32 m0, s44, 0x2000
	s_add_u32 s42, s42, 0x80080
	v_lshl_add_u64 v[202:203], v[204:205], 0, s[66:67]
	s_addc_u32 s43, s43, 0
	s_add_i32 s44, s73, s51
	global_load_lds_dwordx4 v[202:203], off
	v_lshl_add_u64 v[202:203], s[42:43], 0, v[2:3]
	s_mov_b32 m0, s44
	s_nop 0
	global_load_lds_dwordx4 v[202:203], off
	v_lshl_add_u64 v[202:203], s[42:43], 0, v[142:143]
	s_add_i32 m0, s44, 0x2000
	s_nop 0
	global_load_lds_dwordx4 v[202:203], off
	v_lshl_add_u64 v[202:203], v[206:207], 0, s[66:67]
	s_mov_b32 m0, s65
	s_nop 0
	global_load_lds_dwordx4 v[202:203], off
	v_lshl_add_u64 v[202:203], v[220:221], 0, s[66:67]
	s_mov_b32 m0, s68
	s_nop 0
	global_load_lds_dwordx4 v[202:203], off
	s_waitcnt vmcnt(8)
	s_waitcnt lgkmcnt(0)
	s_barrier
	s_setprio 1
	s_waitcnt lgkmcnt(0)
	v_mfma_f32_16x16x32_bf16 v[64:67], v[132:135], v[182:185], v[64:67]
	v_mfma_f32_16x16x32_bf16 v[60:63], v[152:155], v[182:185], v[60:63]
	v_mfma_f32_16x16x32_bf16 v[56:59], v[132:135], v[190:193], v[56:59]
	v_mfma_f32_16x16x32_bf16 v[48:51], v[152:155], v[190:193], v[48:51]
	v_mfma_f32_16x16x32_bf16 v[40:43], v[132:135], v[198:201], v[40:43]
	v_mfma_f32_16x16x32_bf16 v[32:35], v[152:155], v[198:201], v[32:35]
	v_mfma_f32_16x16x32_bf16 v[24:27], v[132:135], v[212:215], v[24:27]
	v_mfma_f32_16x16x32_bf16 v[16:19], v[152:155], v[212:215], v[16:19]
	v_mfma_f32_16x16x32_bf16 v[64:67], v[136:139], v[186:189], v[64:67]
	v_mfma_f32_16x16x32_bf16 v[60:63], v[156:159], v[186:189], v[60:63]
	v_mfma_f32_16x16x32_bf16 v[56:59], v[136:139], v[194:197], v[56:59]
	v_mfma_f32_16x16x32_bf16 v[48:51], v[156:159], v[194:197], v[48:51]
	v_mfma_f32_16x16x32_bf16 v[40:43], v[136:139], v[208:211], v[40:43]
	v_mfma_f32_16x16x32_bf16 v[32:35], v[156:159], v[208:211], v[32:35]
	v_mfma_f32_16x16x32_bf16 v[24:27], v[136:139], v[216:219], v[24:27]
	v_mfma_f32_16x16x32_bf16 v[16:19], v[156:159], v[216:219], v[16:19]
	s_setprio 0
	s_setprio 1
	v_mfma_f32_16x16x32_bf16 v[52:55], v[160:163], v[182:185], v[52:55]
	v_mfma_f32_16x16x32_bf16 v[44:47], v[174:177], v[182:185], v[44:47]
	v_mfma_f32_16x16x32_bf16 v[36:39], v[160:163], v[190:193], v[36:39]
	v_mfma_f32_16x16x32_bf16 v[28:31], v[174:177], v[190:193], v[28:31]
	v_mfma_f32_16x16x32_bf16 v[20:23], v[160:163], v[198:201], v[20:23]
	v_mfma_f32_16x16x32_bf16 v[12:15], v[174:177], v[198:201], v[12:15]
	v_mfma_f32_16x16x32_bf16 v[8:11], v[160:163], v[212:215], v[8:11]
	v_mfma_f32_16x16x32_bf16 v[4:7], v[174:177], v[212:215], v[4:7]
	v_mfma_f32_16x16x32_bf16 v[52:55], v[164:167], v[186:189], v[52:55]
	v_mfma_f32_16x16x32_bf16 v[44:47], v[178:181], v[186:189], v[44:47]
	v_mfma_f32_16x16x32_bf16 v[36:39], v[164:167], v[194:197], v[36:39]
	v_mfma_f32_16x16x32_bf16 v[28:31], v[178:181], v[194:197], v[28:31]
	v_mfma_f32_16x16x32_bf16 v[20:23], v[164:167], v[208:211], v[20:23]
	v_mfma_f32_16x16x32_bf16 v[12:15], v[178:181], v[208:211], v[12:15]
	v_mfma_f32_16x16x32_bf16 v[8:11], v[164:167], v[216:219], v[8:11]
	v_mfma_f32_16x16x32_bf16 v[4:7], v[178:181], v[216:219], v[4:7]
	s_setprio 0
	s_barrier
	s_add_i32 s63, s63, 2
	s_add_u32 s40, s40, 0x100
	s_addc_u32 s41, s41, 0
	s_add_u32 s31, s31, 0x100
	s_addc_u32 s62, s62, 0
	s_cmp_gt_u32 s63, 29
	s_cbranch_scc0 .LBB0_147
	s_and_b64 vcc, exec, s[18:19]
	s_cbranch_vccz .LBB0_150
	s_barrier

.LBB0_211:
	s_sleep 2
	s_add_u32 s30, s28, 0xfff80080
	s_addc_u32 s31, s29, -1
	s_add_i32 s58, 0, 0x10000
	s_cmp_eq_u32 s57, 28
	s_cselect_b32 s39, s21, s31
	s_cselect_b32 s38, s53, s30
	v_add_u32_e32 v148, s58, v151
	s_cselect_b32 s31, s19, s56
	s_cselect_b32 s30, s54, s55
	s_add_i32 s60, 0, 0x14000
	ds_read_b128 v[140:143], v148
	ds_read_b128 v[144:147], v148 offset:1024
	ds_read_b128 v[156:159], v148 offset:2048
	ds_read_b128 v[160:163], v148 offset:3072
	v_add_u32_e32 v148, s60, v151
	ds_read_b128 v[164:167], v148
	ds_read_b128 v[168:171], v148 offset:1024
	ds_read_b128 v[172:175], v148 offset:2048
	ds_read_b128 v[176:179], v148 offset:3072
	s_add_i32 m0, s43, 0xc000
	ds_read_b128 v[180:183], v154
	ds_read_b128 v[184:187], v154 offset:1024
	ds_read_b128 v[188:191], v154 offset:2048
	ds_read_b128 v[192:195], v154 offset:3072
	ds_read_b128 v[196:199], v154 offset:4096
	ds_read_b128 v[200:203], v154 offset:5120
	ds_read_b128 v[208:211], v154 offset:6144
	ds_read_b128 v[212:215], v154 offset:7168
	global_load_lds_dwordx4 v136, s[28:29]
	s_add_i32 m0, s43, 0xe000
	s_nop 0
	global_load_lds_dwordx4 v138, s[28:29]
	s_waitcnt vmcnt(8)
	s_waitcnt lgkmcnt(0)
	s_barrier
	s_setprio 1
	s_waitcnt lgkmcnt(0)
	v_mfma_f32_16x16x32_bf16 v[128:131], v[140:143], v[180:183], v[128:131]
	v_mfma_f32_16x16x32_bf16 v[124:127], v[156:159], v[180:183], v[124:127]
	v_mfma_f32_16x16x32_bf16 v[112:115], v[140:143], v[188:191], v[112:115]
	v_mfma_f32_16x16x32_bf16 v[108:111], v[156:159], v[188:191], v[108:111]
	v_mfma_f32_16x16x32_bf16 v[96:99], v[140:143], v[196:199], v[96:99]
	v_mfma_f32_16x16x32_bf16 v[92:95], v[156:159], v[196:199], v[92:95]
	v_mfma_f32_16x16x32_bf16 v[80:83], v[140:143], v[208:211], v[80:83]
	v_mfma_f32_16x16x32_bf16 v[76:79], v[156:159], v[208:211], v[76:79]
	v_mfma_f32_16x16x32_bf16 v[128:131], v[144:147], v[184:187], v[128:131]
	v_mfma_f32_16x16x32_bf16 v[124:127], v[160:163], v[184:187], v[124:127]
	v_mfma_f32_16x16x32_bf16 v[112:115], v[144:147], v[192:195], v[112:115]
	v_mfma_f32_16x16x32_bf16 v[108:111], v[160:163], v[192:195], v[108:111]
	v_mfma_f32_16x16x32_bf16 v[96:99], v[144:147], v[200:203], v[96:99]
	v_mfma_f32_16x16x32_bf16 v[92:95], v[160:163], v[200:203], v[92:95]
	v_mfma_f32_16x16x32_bf16 v[80:83], v[144:147], v[212:215], v[80:83]
	v_mfma_f32_16x16x32_bf16 v[76:79], v[160:163], v[212:215], v[76:79]
	s_setprio 0
	s_setprio 1
	v_mfma_f32_16x16x32_bf16 v[120:123], v[164:167], v[180:183], v[120:123]
	v_mfma_f32_16x16x32_bf16 v[116:119], v[172:175], v[180:183], v[116:119]
	v_mfma_f32_16x16x32_bf16 v[104:107], v[164:167], v[188:191], v[104:107]
	v_mfma_f32_16x16x32_bf16 v[100:103], v[172:175], v[188:191], v[100:103]
	v_mfma_f32_16x16x32_bf16 v[88:91], v[164:167], v[196:199], v[88:91]
	v_mfma_f32_16x16x32_bf16 v[84:87], v[172:175], v[196:199], v[84:87]
	v_mfma_f32_16x16x32_bf16 v[72:75], v[164:167], v[208:211], v[72:75]
	v_mfma_f32_16x16x32_bf16 v[68:71], v[172:175], v[208:211], v[68:71]
	v_mfma_f32_16x16x32_bf16 v[120:123], v[168:171], v[184:187], v[120:123]
	v_mfma_f32_16x16x32_bf16 v[116:119], v[176:179], v[184:187], v[116:119]
	v_mfma_f32_16x16x32_bf16 v[104:107], v[168:171], v[192:195], v[104:107]
	v_mfma_f32_16x16x32_bf16 v[100:103], v[176:179], v[192:195], v[100:103]
	v_mfma_f32_16x16x32_bf16 v[88:91], v[168:171], v[200:203], v[88:91]
	v_mfma_f32_16x16x32_bf16 v[84:87], v[176:179], v[200:203], v[84:87]
	v_mfma_f32_16x16x32_bf16 v[72:75], v[168:171], v[212:215], v[72:75]
	v_mfma_f32_16x16x32_bf16 v[68:71], v[176:179], v[212:215], v[68:71]
	s_setprio 0
	s_barrier
	s_sleep 2
	s_add_i32 s58, s58, s41
	s_mov_b32 m0, s58
	ds_read_b128 v[180:183], v154 offset:16384
	ds_read_b128 v[184:187], v154 offset:17408
	ds_read_b128 v[188:191], v154 offset:18432
	ds_read_b128 v[192:195], v154 offset:19456
	ds_read_b128 v[196:199], v154 offset:20480
	ds_read_b128 v[200:203], v154 offset:21504
	ds_read_b128 v[208:211], v154 offset:22528
	ds_read_b128 v[212:215], v154 offset:23552
	global_load_lds_dwordx4 v2, s[30:31]
	s_add_i32 m0, s58, 0x2000
	s_add_u32 s62, s30, 0x80000
	s_addc_u32 s63, s31, 0
	s_add_i32 s58, s60, s41
	global_load_lds_dwordx4 v0, s[30:31]
	s_mov_b32 m0, s58
	s_nop 0
	global_load_lds_dwordx4 v2, s[62:63]
	s_add_i32 m0, s58, 0x2000
	s_nop 0
	global_load_lds_dwordx4 v0, s[62:63]
	s_mov_b32 m0, s43
	s_nop 0
	global_load_lds_dwordx4 v134, s[38:39]
	s_mov_b32 m0, s44
	s_nop 0
	global_load_lds_dwordx4 v132, s[38:39]
	s_waitcnt vmcnt(8)
	s_waitcnt lgkmcnt(0)
	s_barrier
	s_setprio 1
	s_waitcnt lgkmcnt(0)
	v_mfma_f32_16x16x32_bf16 v[64:67], v[140:143], v[180:183], v[64:67]
	v_mfma_f32_16x16x32_bf16 v[60:63], v[156:159], v[180:183], v[60:63]
	v_mfma_f32_16x16x32_bf16 v[48:51], v[140:143], v[188:191], v[48:51]
	v_mfma_f32_16x16x32_bf16 v[44:47], v[156:159], v[188:191], v[44:47]
	v_mfma_f32_16x16x32_bf16 v[32:35], v[140:143], v[196:199], v[32:35]
	v_mfma_f32_16x16x32_bf16 v[28:31], v[156:159], v[196:199], v[28:31]
	v_mfma_f32_16x16x32_bf16 v[16:19], v[140:143], v[208:211], v[16:19]
	v_mfma_f32_16x16x32_bf16 v[12:15], v[156:159], v[208:211], v[12:15]
	v_mfma_f32_16x16x32_bf16 v[64:67], v[144:147], v[184:187], v[64:67]
	v_mfma_f32_16x16x32_bf16 v[60:63], v[160:163], v[184:187], v[60:63]
	v_mfma_f32_16x16x32_bf16 v[48:51], v[144:147], v[192:195], v[48:51]
	v_mfma_f32_16x16x32_bf16 v[44:47], v[160:163], v[192:195], v[44:47]
	v_mfma_f32_16x16x32_bf16 v[32:35], v[144:147], v[200:203], v[32:35]
	v_mfma_f32_16x16x32_bf16 v[28:31], v[160:163], v[200:203], v[28:31]
	v_mfma_f32_16x16x32_bf16 v[16:19], v[144:147], v[212:215], v[16:19]
	v_mfma_f32_16x16x32_bf16 v[12:15], v[160:163], v[212:215], v[12:15]
	s_setprio 0
	s_setprio 1
	v_mfma_f32_16x16x32_bf16 v[56:59], v[164:167], v[180:183], v[56:59]
	v_mfma_f32_16x16x32_bf16 v[52:55], v[172:175], v[180:183], v[52:55]
	v_mfma_f32_16x16x32_bf16 v[40:43], v[164:167], v[188:191], v[40:43]
	v_mfma_f32_16x16x32_bf16 v[36:39], v[172:175], v[188:191], v[36:39]
	v_mfma_f32_16x16x32_bf16 v[24:27], v[164:167], v[196:199], v[24:27]
	v_mfma_f32_16x16x32_bf16 v[20:23], v[172:175], v[196:199], v[20:23]
	v_mfma_f32_16x16x32_bf16 v[8:11], v[164:167], v[208:211], v[8:11]
	v_mfma_f32_16x16x32_bf16 v[4:7], v[172:175], v[208:211], v[4:7]
	v_mfma_f32_16x16x32_bf16 v[56:59], v[168:171], v[184:187], v[56:59]
	v_mfma_f32_16x16x32_bf16 v[52:55], v[176:179], v[184:187], v[52:55]
	v_mfma_f32_16x16x32_bf16 v[40:43], v[168:171], v[192:195], v[40:43]
	v_mfma_f32_16x16x32_bf16 v[36:39], v[176:179], v[192:195], v[36:39]
	v_mfma_f32_16x16x32_bf16 v[24:27], v[168:171], v[200:203], v[24:27]
	v_mfma_f32_16x16x32_bf16 v[20:23], v[176:179], v[200:203], v[20:23]
	v_mfma_f32_16x16x32_bf16 v[8:11], v[168:171], v[212:215], v[8:11]
	v_mfma_f32_16x16x32_bf16 v[4:7], v[176:179], v[212:215], v[4:7]
	s_setprio 0
	s_barrier
	s_sleep 2
	s_add_i32 s58, 0, 0x18000
	v_add_u32_e32 v155, s58, v151
	s_add_i32 s60, 0, 0x1c000
	ds_read_b128 v[140:143], v155
	ds_read_b128 v[144:147], v155 offset:1024
	ds_read_b128 v[156:159], v155 offset:2048
	ds_read_b128 v[160:163], v155 offset:3072
	v_add_u32_e32 v155, s60, v151
	ds_read_b128 v[164:167], v155
	ds_read_b128 v[168:171], v155 offset:1024
	ds_read_b128 v[172:175], v155 offset:2048
	ds_read_b128 v[176:179], v155 offset:3072
	s_add_u32 s38, s38, 0x80000
	s_addc_u32 s39, s39, 0
	s_mov_b32 m0, s45
	ds_read_b128 v[180:183], v154 offset:32768
	ds_read_b128 v[184:187], v154 offset:33792
	ds_read_b128 v[188:191], v154 offset:34816
	ds_read_b128 v[192:195], v154 offset:35840
	ds_read_b128 v[196:199], v154 offset:36864
	ds_read_b128 v[200:203], v154 offset:37888
	ds_read_b128 v[208:211], v154 offset:38912
	ds_read_b128 v[212:215], v154 offset:39936
	global_load_lds_dwordx4 v134, s[38:39]
	s_mov_b32 m0, s47
	s_nop 0
	global_load_lds_dwordx4 v132, s[38:39]
	s_waitcnt vmcnt(8)
	s_waitcnt lgkmcnt(0)
	s_barrier
	s_setprio 1
	s_waitcnt lgkmcnt(0)
	v_mfma_f32_16x16x32_bf16 v[128:131], v[140:143], v[180:183], v[128:131]
	v_mfma_f32_16x16x32_bf16 v[124:127], v[156:159], v[180:183], v[124:127]
	v_mfma_f32_16x16x32_bf16 v[112:115], v[140:143], v[188:191], v[112:115]
	v_mfma_f32_16x16x32_bf16 v[108:111], v[156:159], v[188:191], v[108:111]
	v_mfma_f32_16x16x32_bf16 v[96:99], v[140:143], v[196:199], v[96:99]
	v_mfma_f32_16x16x32_bf16 v[92:95], v[156:159], v[196:199], v[92:95]
	v_mfma_f32_16x16x32_bf16 v[80:83], v[140:143], v[208:211], v[80:83]
	v_mfma_f32_16x16x32_bf16 v[76:79], v[156:159], v[208:211], v[76:79]
	v_mfma_f32_16x16x32_bf16 v[128:131], v[144:147], v[184:187], v[128:131]
	v_mfma_f32_16x16x32_bf16 v[124:127], v[160:163], v[184:187], v[124:127]
	v_mfma_f32_16x16x32_bf16 v[112:115], v[144:147], v[192:195], v[112:115]
	v_mfma_f32_16x16x32_bf16 v[108:111], v[160:163], v[192:195], v[108:111]
	v_mfma_f32_16x16x32_bf16 v[96:99], v[144:147], v[200:203], v[96:99]
	v_mfma_f32_16x16x32_bf16 v[92:95], v[160:163], v[200:203], v[92:95]
	v_mfma_f32_16x16x32_bf16 v[80:83], v[144:147], v[212:215], v[80:83]
	v_mfma_f32_16x16x32_bf16 v[76:79], v[160:163], v[212:215], v[76:79]
	s_setprio 0
	s_setprio 1
	v_mfma_f32_16x16x32_bf16 v[120:123], v[164:167], v[180:183], v[120:123]
	v_mfma_f32_16x16x32_bf16 v[116:119], v[172:175], v[180:183], v[116:119]
	v_mfma_f32_16x16x32_bf16 v[104:107], v[164:167], v[188:191], v[104:107]
	v_mfma_f32_16x16x32_bf16 v[100:103], v[172:175], v[188:191], v[100:103]
	v_mfma_f32_16x16x32_bf16 v[88:91], v[164:167], v[196:199], v[88:91]
	v_mfma_f32_16x16x32_bf16 v[84:87], v[172:175], v[196:199], v[84:87]
	v_mfma_f32_16x16x32_bf16 v[72:75], v[164:167], v[208:211], v[72:75]
	v_mfma_f32_16x16x32_bf16 v[68:71], v[172:175], v[208:211], v[68:71]
	v_mfma_f32_16x16x32_bf16 v[120:123], v[168:171], v[184:187], v[120:123]
	v_mfma_f32_16x16x32_bf16 v[116:119], v[176:179], v[184:187], v[116:119]
	v_mfma_f32_16x16x32_bf16 v[104:107], v[168:171], v[192:195], v[104:107]
	v_mfma_f32_16x16x32_bf16 v[100:103], v[176:179], v[192:195], v[100:103]
	v_mfma_f32_16x16x32_bf16 v[88:91], v[168:171], v[200:203], v[88:91]
	v_mfma_f32_16x16x32_bf16 v[84:87], v[176:179], v[200:203], v[84:87]
	v_mfma_f32_16x16x32_bf16 v[72:75], v[168:171], v[212:215], v[72:75]
	v_mfma_f32_16x16x32_bf16 v[68:71], v[176:179], v[212:215], v[68:71]
	s_setprio 0
	s_barrier
	s_sleep 2
	s_add_i32 s62, s58, s41
	s_add_u32 s30, s30, 0x80
	s_addc_u32 s31, s31, 0
	s_mov_b32 m0, s62
	ds_read_b128 v[180:183], v154 offset:49152
	ds_read_b128 v[184:187], v154 offset:50176
	ds_read_b128 v[188:191], v154 offset:51200
	ds_read_b128 v[192:195], v154 offset:52224
	ds_read_b128 v[196:199], v154 offset:53248
	ds_read_b128 v[200:203], v154 offset:54272
	ds_read_b128 v[208:211], v154 offset:55296
	ds_read_b128 v[212:215], v154 offset:56320
	global_load_lds_dwordx4 v2, s[30:31]
	s_add_i32 m0, s62, 0x2000
	s_nop 0
	s_add_i32 s62, s60, s41
	global_load_lds_dwordx4 v0, s[30:31]
	s_add_u32 s30, s30, 0x80000
	s_addc_u32 s31, s31, 0
	s_mov_b32 m0, s62
	s_nop 0
	global_load_lds_dwordx4 v2, s[30:31]
	s_add_i32 m0, s62, 0x2000
	s_nop 0
	global_load_lds_dwordx4 v0, s[30:31]
	s_sub_u32 s38, s38, 0x7ff80
	s_subb_u32 s39, s39, 0
	s_mov_b32 m0, s48
	s_nop 0
	global_load_lds_dwordx4 v134, s[38:39]
	s_mov_b32 m0, s49
	s_nop 0
	global_load_lds_dwordx4 v132, s[38:39]
	s_waitcnt vmcnt(8)
	s_waitcnt lgkmcnt(0)
	s_barrier
	s_setprio 1
	s_waitcnt lgkmcnt(0)
	v_mfma_f32_16x16x32_bf16 v[64:67], v[140:143], v[180:183], v[64:67]
	v_mfma_f32_16x16x32_bf16 v[60:63], v[156:159], v[180:183], v[60:63]
	v_mfma_f32_16x16x32_bf16 v[48:51], v[140:143], v[188:191], v[48:51]
	v_mfma_f32_16x16x32_bf16 v[44:47], v[156:159], v[188:191], v[44:47]
	v_mfma_f32_16x16x32_bf16 v[32:35], v[140:143], v[196:199], v[32:35]
	v_mfma_f32_16x16x32_bf16 v[28:31], v[156:159], v[196:199], v[28:31]
	v_mfma_f32_16x16x32_bf16 v[16:19], v[140:143], v[208:211], v[16:19]
	v_mfma_f32_16x16x32_bf16 v[12:15], v[156:159], v[208:211], v[12:15]
	v_mfma_f32_16x16x32_bf16 v[64:67], v[144:147], v[184:187], v[64:67]
	v_mfma_f32_16x16x32_bf16 v[60:63], v[160:163], v[184:187], v[60:63]
	v_mfma_f32_16x16x32_bf16 v[48:51], v[144:147], v[192:195], v[48:51]
	v_mfma_f32_16x16x32_bf16 v[44:47], v[160:163], v[192:195], v[44:47]
	v_mfma_f32_16x16x32_bf16 v[32:35], v[144:147], v[200:203], v[32:35]
	v_mfma_f32_16x16x32_bf16 v[28:31], v[160:163], v[200:203], v[28:31]
	v_mfma_f32_16x16x32_bf16 v[16:19], v[144:147], v[212:215], v[16:19]
	v_mfma_f32_16x16x32_bf16 v[12:15], v[160:163], v[212:215], v[12:15]
	s_setprio 0
	s_setprio 1
	v_mfma_f32_16x16x32_bf16 v[56:59], v[164:167], v[180:183], v[56:59]
	v_mfma_f32_16x16x32_bf16 v[52:55], v[172:175], v[180:183], v[52:55]
	v_mfma_f32_16x16x32_bf16 v[40:43], v[164:167], v[188:191], v[40:43]
	v_mfma_f32_16x16x32_bf16 v[36:39], v[172:175], v[188:191], v[36:39]
	v_mfma_f32_16x16x32_bf16 v[24:27], v[164:167], v[196:199], v[24:27]
	v_mfma_f32_16x16x32_bf16 v[20:23], v[172:175], v[196:199], v[20:23]
	v_mfma_f32_16x16x32_bf16 v[8:11], v[164:167], v[208:211], v[8:11]
	v_mfma_f32_16x16x32_bf16 v[4:7], v[172:175], v[208:211], v[4:7]
	v_mfma_f32_16x16x32_bf16 v[56:59], v[168:171], v[184:187], v[56:59]
	v_mfma_f32_16x16x32_bf16 v[52:55], v[176:179], v[184:187], v[52:55]
	v_mfma_f32_16x16x32_bf16 v[40:43], v[168:171], v[192:195], v[40:43]
	v_mfma_f32_16x16x32_bf16 v[36:39], v[176:179], v[192:195], v[36:39]
	v_mfma_f32_16x16x32_bf16 v[24:27], v[168:171], v[200:203], v[24:27]
	v_mfma_f32_16x16x32_bf16 v[20:23], v[176:179], v[200:203], v[20:23]
	v_mfma_f32_16x16x32_bf16 v[8:11], v[168:171], v[212:215], v[8:11]
	v_mfma_f32_16x16x32_bf16 v[4:7], v[176:179], v[212:215], v[4:7]
	s_setprio 0
	s_barrier
	s_add_i32 s57, s57, 2
	s_add_u32 s28, s28, 0x100
	s_addc_u32 s29, s29, 0
	s_add_u32 s55, s55, 0x100
	s_addc_u32 s56, s56, 0
	s_cmp_gt_u32 s57, 29
	s_cbranch_scc0 .LBB0_211
	s_and_b64 vcc, exec, s[16:17]
	s_cbranch_vccz .LBB0_214
	s_barrier

.LBB0_301:
	s_sleep 2
	s_add_u32 s18, s16, 0x100
	s_addc_u32 s19, s17, 0
	s_add_i32 s49, 0, 0x10000
	s_cmpk_eq_i32 s48, 0x54
	s_cselect_b32 s23, s13, s19
	s_cselect_b32 s22, s12, s18
	s_cselect_b32 s21, s15, s41
	s_cselect_b32 s20, s14, s40
	s_add_i32 s50, 0, 0x14000
	v_add_u32_e32 v144, s49, v219
	v_add_u32_e32 v160, s50, v219
	ds_read_b128 v[124:127], v144
	ds_read_b128 v[128:131], v144 offset:1024
	ds_read_b128 v[140:143], v144 offset:2048
	ds_read_b128 v[144:147], v144 offset:3072
	ds_read_b128 v[148:151], v160
	ds_read_b128 v[152:155], v160 offset:1024
	ds_read_b128 v[156:159], v160 offset:2048
	ds_read_b128 v[160:163], v160 offset:3072
	v_lshl_add_u64 v[204:205], s[16:17], 0, v[192:193]
	s_add_i32 m0, s28, 0xc000
	ds_read_b128 v[164:167], v221
	ds_read_b128 v[168:171], v221 offset:1024
	ds_read_b128 v[172:175], v221 offset:2048
	ds_read_b128 v[176:179], v221 offset:3072
	ds_read_b128 v[180:183], v221 offset:4096
	ds_read_b128 v[184:187], v221 offset:5120
	ds_read_b128 v[196:199], v221 offset:6144
	ds_read_b128 v[200:203], v221 offset:7168
	global_load_lds_dwordx4 v[204:205], off
	v_lshl_add_u64 v[204:205], s[16:17], 0, v[194:195]
	s_add_i32 m0, s28, 0xe000
	s_nop 0
	global_load_lds_dwordx4 v[204:205], off
	s_waitcnt vmcnt(8)
	s_waitcnt lgkmcnt(0)
	s_barrier
	s_setprio 1
	s_waitcnt lgkmcnt(0)
	v_mfma_f32_16x16x32_bf16 v[136:139], v[124:127], v[164:167], v[136:139]
	v_mfma_f32_16x16x32_bf16 v[132:135], v[140:143], v[164:167], v[132:135]
	v_mfma_f32_16x16x32_bf16 v[112:115], v[124:127], v[172:175], v[112:115]
	v_mfma_f32_16x16x32_bf16 v[108:111], v[140:143], v[172:175], v[108:111]
	v_mfma_f32_16x16x32_bf16 v[96:99], v[124:127], v[180:183], v[96:99]
	v_mfma_f32_16x16x32_bf16 v[92:95], v[140:143], v[180:183], v[92:95]
	v_mfma_f32_16x16x32_bf16 v[80:83], v[124:127], v[196:199], v[80:83]
	v_mfma_f32_16x16x32_bf16 v[76:79], v[140:143], v[196:199], v[76:79]
	v_mfma_f32_16x16x32_bf16 v[136:139], v[128:131], v[168:171], v[136:139]
	v_mfma_f32_16x16x32_bf16 v[132:135], v[144:147], v[168:171], v[132:135]
	v_mfma_f32_16x16x32_bf16 v[112:115], v[128:131], v[176:179], v[112:115]
	v_mfma_f32_16x16x32_bf16 v[108:111], v[144:147], v[176:179], v[108:111]
	v_mfma_f32_16x16x32_bf16 v[96:99], v[128:131], v[184:187], v[96:99]
	v_mfma_f32_16x16x32_bf16 v[92:95], v[144:147], v[184:187], v[92:95]
	v_mfma_f32_16x16x32_bf16 v[80:83], v[128:131], v[200:203], v[80:83]
	v_mfma_f32_16x16x32_bf16 v[76:79], v[144:147], v[200:203], v[76:79]
	s_setprio 0
	s_setprio 1
	v_mfma_f32_16x16x32_bf16 v[120:123], v[148:151], v[164:167], v[120:123]
	v_mfma_f32_16x16x32_bf16 v[116:119], v[156:159], v[164:167], v[116:119]
	v_mfma_f32_16x16x32_bf16 v[104:107], v[148:151], v[172:175], v[104:107]
	v_mfma_f32_16x16x32_bf16 v[100:103], v[156:159], v[172:175], v[100:103]
	v_mfma_f32_16x16x32_bf16 v[88:91], v[148:151], v[180:183], v[88:91]
	v_mfma_f32_16x16x32_bf16 v[84:87], v[156:159], v[180:183], v[84:87]
	v_mfma_f32_16x16x32_bf16 v[72:75], v[148:151], v[196:199], v[72:75]
	v_mfma_f32_16x16x32_bf16 v[68:71], v[156:159], v[196:199], v[68:71]
	v_mfma_f32_16x16x32_bf16 v[120:123], v[152:155], v[168:171], v[120:123]
	v_mfma_f32_16x16x32_bf16 v[116:119], v[160:163], v[168:171], v[116:119]
	v_mfma_f32_16x16x32_bf16 v[104:107], v[152:155], v[176:179], v[104:107]
	v_mfma_f32_16x16x32_bf16 v[100:103], v[160:163], v[176:179], v[100:103]
	v_mfma_f32_16x16x32_bf16 v[88:91], v[152:155], v[184:187], v[88:91]
	v_mfma_f32_16x16x32_bf16 v[84:87], v[160:163], v[184:187], v[84:87]
	v_mfma_f32_16x16x32_bf16 v[72:75], v[152:155], v[200:203], v[72:75]
	v_mfma_f32_16x16x32_bf16 v[68:71], v[160:163], v[200:203], v[68:71]
	s_setprio 0
	s_barrier
	s_sleep 2
	s_add_i32 s16, s49, s2
	v_lshl_add_u64 v[204:205], s[20:21], 0, v[2:3]
	s_mov_b32 m0, s16
	ds_read_b128 v[164:167], v221 offset:16384
	ds_read_b128 v[168:171], v221 offset:17408
	ds_read_b128 v[172:175], v221 offset:18432
	ds_read_b128 v[176:179], v221 offset:19456
	ds_read_b128 v[180:183], v221 offset:20480
	ds_read_b128 v[184:187], v221 offset:21504
	ds_read_b128 v[196:199], v221 offset:22528
	ds_read_b128 v[200:203], v221 offset:23552
	global_load_lds_dwordx4 v[204:205], off
	s_add_i32 m0, s16, 0x2000
	s_add_u32 s16, s20, 0x160000
	v_lshl_add_u64 v[206:207], s[20:21], 0, v[190:191]
	s_addc_u32 s17, s21, 0
	s_add_i32 s49, s50, s2
	global_load_lds_dwordx4 v[206:207], off
	v_lshl_add_u64 v[208:209], s[16:17], 0, v[2:3]
	s_mov_b32 m0, s49
	v_lshl_add_u64 v[210:211], s[22:23], 0, v[188:189]
	global_load_lds_dwordx4 v[208:209], off
	v_lshl_add_u64 v[208:209], s[16:17], 0, v[190:191]
	s_add_i32 m0, s49, 0x2000
	s_nop 0
	global_load_lds_dwordx4 v[208:209], off
	v_lshl_add_u64 v[208:209], s[22:23], 0, v[0:1]
	s_mov_b32 m0, s28
	s_nop 0
	global_load_lds_dwordx4 v[208:209], off
	s_mov_b32 m0, s29
	s_nop 0
	global_load_lds_dwordx4 v[210:211], off
	s_waitcnt vmcnt(8)
	s_waitcnt lgkmcnt(0)
	s_barrier
	s_setprio 1
	s_waitcnt lgkmcnt(0)
	v_mfma_f32_16x16x32_bf16 v[64:67], v[124:127], v[164:167], v[64:67]
	v_mfma_f32_16x16x32_bf16 v[60:63], v[140:143], v[164:167], v[60:63]
	v_mfma_f32_16x16x32_bf16 v[48:51], v[124:127], v[172:175], v[48:51]
	v_mfma_f32_16x16x32_bf16 v[44:47], v[140:143], v[172:175], v[44:47]
	v_mfma_f32_16x16x32_bf16 v[32:35], v[124:127], v[180:183], v[32:35]
	v_mfma_f32_16x16x32_bf16 v[28:31], v[140:143], v[180:183], v[28:31]
	v_mfma_f32_16x16x32_bf16 v[16:19], v[124:127], v[196:199], v[16:19]
	v_mfma_f32_16x16x32_bf16 v[12:15], v[140:143], v[196:199], v[12:15]
	v_mfma_f32_16x16x32_bf16 v[64:67], v[128:131], v[168:171], v[64:67]
	v_mfma_f32_16x16x32_bf16 v[60:63], v[144:147], v[168:171], v[60:63]
	v_mfma_f32_16x16x32_bf16 v[48:51], v[128:131], v[176:179], v[48:51]
	v_mfma_f32_16x16x32_bf16 v[44:47], v[144:147], v[176:179], v[44:47]
	v_mfma_f32_16x16x32_bf16 v[32:35], v[128:131], v[184:187], v[32:35]
	v_mfma_f32_16x16x32_bf16 v[28:31], v[144:147], v[184:187], v[28:31]
	v_mfma_f32_16x16x32_bf16 v[16:19], v[128:131], v[200:203], v[16:19]
	v_mfma_f32_16x16x32_bf16 v[12:15], v[144:147], v[200:203], v[12:15]
	s_setprio 0
	s_setprio 1
	v_mfma_f32_16x16x32_bf16 v[56:59], v[148:151], v[164:167], v[56:59]
	v_mfma_f32_16x16x32_bf16 v[52:55], v[156:159], v[164:167], v[52:55]
	v_mfma_f32_16x16x32_bf16 v[40:43], v[148:151], v[172:175], v[40:43]
	v_mfma_f32_16x16x32_bf16 v[36:39], v[156:159], v[172:175], v[36:39]
	v_mfma_f32_16x16x32_bf16 v[24:27], v[148:151], v[180:183], v[24:27]
	v_mfma_f32_16x16x32_bf16 v[20:23], v[156:159], v[180:183], v[20:23]
	v_mfma_f32_16x16x32_bf16 v[8:11], v[148:151], v[196:199], v[8:11]
	v_mfma_f32_16x16x32_bf16 v[4:7], v[156:159], v[196:199], v[4:7]
	v_mfma_f32_16x16x32_bf16 v[56:59], v[152:155], v[168:171], v[56:59]
	v_mfma_f32_16x16x32_bf16 v[52:55], v[160:163], v[168:171], v[52:55]
	v_mfma_f32_16x16x32_bf16 v[40:43], v[152:155], v[176:179], v[40:43]
	v_mfma_f32_16x16x32_bf16 v[36:39], v[160:163], v[176:179], v[36:39]
	v_mfma_f32_16x16x32_bf16 v[24:27], v[152:155], v[184:187], v[24:27]
	v_mfma_f32_16x16x32_bf16 v[20:23], v[160:163], v[184:187], v[20:23]
	v_mfma_f32_16x16x32_bf16 v[8:11], v[152:155], v[200:203], v[8:11]
	v_mfma_f32_16x16x32_bf16 v[4:7], v[160:163], v[200:203], v[4:7]
	s_setprio 0
	s_barrier
	s_sleep 2
	s_add_i32 s49, 0, 0x18000
	s_add_i32 s50, 0, 0x1c000
	v_add_u32_e32 v144, s49, v219
	v_add_u32_e32 v160, s50, v219
	ds_read_b128 v[124:127], v144
	ds_read_b128 v[128:131], v144 offset:1024
	ds_read_b128 v[140:143], v144 offset:2048
	ds_read_b128 v[144:147], v144 offset:3072
	ds_read_b128 v[148:151], v160
	ds_read_b128 v[152:155], v160 offset:1024
	ds_read_b128 v[156:159], v160 offset:2048
	ds_read_b128 v[160:163], v160 offset:3072
	s_add_u32 s16, s22, 0x160000
	s_addc_u32 s17, s23, 0
	s_mov_b32 m0, s30
	v_lshl_add_u64 v[212:213], s[16:17], 0, v[0:1]
	ds_read_b128 v[164:167], v221 offset:32768
	ds_read_b128 v[168:171], v221 offset:33792
	ds_read_b128 v[172:175], v221 offset:34816
	ds_read_b128 v[176:179], v221 offset:35840
	ds_read_b128 v[180:183], v221 offset:36864
	ds_read_b128 v[184:187], v221 offset:37888
	ds_read_b128 v[196:199], v221 offset:38912
	ds_read_b128 v[200:203], v221 offset:39936
	global_load_lds_dwordx4 v[212:213], off
	v_lshl_add_u64 v[212:213], s[16:17], 0, v[188:189]
	s_mov_b32 m0, s31
	s_nop 0
	global_load_lds_dwordx4 v[212:213], off
	s_waitcnt vmcnt(8)
	s_waitcnt lgkmcnt(0)
	s_barrier
	s_setprio 1
	s_waitcnt lgkmcnt(0)
	v_mfma_f32_16x16x32_bf16 v[136:139], v[124:127], v[164:167], v[136:139]
	v_mfma_f32_16x16x32_bf16 v[132:135], v[140:143], v[164:167], v[132:135]
	v_mfma_f32_16x16x32_bf16 v[112:115], v[124:127], v[172:175], v[112:115]
	v_mfma_f32_16x16x32_bf16 v[108:111], v[140:143], v[172:175], v[108:111]
	v_mfma_f32_16x16x32_bf16 v[96:99], v[124:127], v[180:183], v[96:99]
	v_mfma_f32_16x16x32_bf16 v[92:95], v[140:143], v[180:183], v[92:95]
	v_mfma_f32_16x16x32_bf16 v[80:83], v[124:127], v[196:199], v[80:83]
	v_mfma_f32_16x16x32_bf16 v[76:79], v[140:143], v[196:199], v[76:79]
	v_mfma_f32_16x16x32_bf16 v[136:139], v[128:131], v[168:171], v[136:139]
	v_mfma_f32_16x16x32_bf16 v[132:135], v[144:147], v[168:171], v[132:135]
	v_mfma_f32_16x16x32_bf16 v[112:115], v[128:131], v[176:179], v[112:115]
	v_mfma_f32_16x16x32_bf16 v[108:111], v[144:147], v[176:179], v[108:111]
	v_mfma_f32_16x16x32_bf16 v[96:99], v[128:131], v[184:187], v[96:99]
	v_mfma_f32_16x16x32_bf16 v[92:95], v[144:147], v[184:187], v[92:95]
	v_mfma_f32_16x16x32_bf16 v[80:83], v[128:131], v[200:203], v[80:83]
	v_mfma_f32_16x16x32_bf16 v[76:79], v[144:147], v[200:203], v[76:79]
	s_setprio 0
	s_setprio 1
	v_mfma_f32_16x16x32_bf16 v[120:123], v[148:151], v[164:167], v[120:123]
	v_mfma_f32_16x16x32_bf16 v[116:119], v[156:159], v[164:167], v[116:119]
	v_mfma_f32_16x16x32_bf16 v[104:107], v[148:151], v[172:175], v[104:107]
	v_mfma_f32_16x16x32_bf16 v[100:103], v[156:159], v[172:175], v[100:103]
	v_mfma_f32_16x16x32_bf16 v[88:91], v[148:151], v[180:183], v[88:91]
	v_mfma_f32_16x16x32_bf16 v[84:87], v[156:159], v[180:183], v[84:87]
	v_mfma_f32_16x16x32_bf16 v[72:75], v[148:151], v[196:199], v[72:75]
	v_mfma_f32_16x16x32_bf16 v[68:71], v[156:159], v[196:199], v[68:71]
	v_mfma_f32_16x16x32_bf16 v[120:123], v[152:155], v[168:171], v[120:123]
	v_mfma_f32_16x16x32_bf16 v[116:119], v[160:163], v[168:171], v[116:119]
	v_mfma_f32_16x16x32_bf16 v[104:107], v[152:155], v[176:179], v[104:107]
	v_mfma_f32_16x16x32_bf16 v[100:103], v[160:163], v[176:179], v[100:103]
	v_mfma_f32_16x16x32_bf16 v[88:91], v[152:155], v[184:187], v[88:91]
	v_mfma_f32_16x16x32_bf16 v[84:87], v[160:163], v[184:187], v[84:87]
	v_mfma_f32_16x16x32_bf16 v[72:75], v[152:155], v[200:203], v[72:75]
	v_mfma_f32_16x16x32_bf16 v[68:71], v[160:163], v[200:203], v[68:71]
	s_setprio 0
	s_barrier
	s_sleep 2
	s_add_i32 s16, s49, s2
	v_lshl_add_u64 v[204:205], v[204:205], 0, s[66:67]
	s_mov_b32 m0, s16
	ds_read_b128 v[164:167], v221 offset:49152
	ds_read_b128 v[168:171], v221 offset:50176
	ds_read_b128 v[172:175], v221 offset:51200
	ds_read_b128 v[176:179], v221 offset:52224
	ds_read_b128 v[180:183], v221 offset:53248
	ds_read_b128 v[184:187], v221 offset:54272
	ds_read_b128 v[196:199], v221 offset:55296
	ds_read_b128 v[200:203], v221 offset:56320
	global_load_lds_dwordx4 v[204:205], off
	s_add_i32 m0, s16, 0x2000
	s_add_u32 s16, s20, 0x160080
	v_lshl_add_u64 v[204:205], v[206:207], 0, s[66:67]
	s_addc_u32 s17, s21, 0
	s_add_i32 s20, s50, s2
	global_load_lds_dwordx4 v[204:205], off
	v_lshl_add_u64 v[204:205], s[16:17], 0, v[2:3]
	s_mov_b32 m0, s20
	s_nop 0
	global_load_lds_dwordx4 v[204:205], off
	v_lshl_add_u64 v[204:205], s[16:17], 0, v[190:191]
	s_add_i32 m0, s20, 0x2000
	s_nop 0
	global_load_lds_dwordx4 v[204:205], off
	v_lshl_add_u64 v[204:205], v[208:209], 0, s[66:67]
	s_mov_b32 m0, s34
	s_nop 0
	global_load_lds_dwordx4 v[204:205], off
	v_lshl_add_u64 v[204:205], v[210:211], 0, s[66:67]
	s_mov_b32 m0, s35
	s_nop 0
	global_load_lds_dwordx4 v[204:205], off
	s_waitcnt vmcnt(8)
	s_waitcnt lgkmcnt(0)
	s_barrier
	s_setprio 1
	s_waitcnt lgkmcnt(0)
	v_mfma_f32_16x16x32_bf16 v[64:67], v[124:127], v[164:167], v[64:67]
	v_mfma_f32_16x16x32_bf16 v[60:63], v[140:143], v[164:167], v[60:63]
	v_mfma_f32_16x16x32_bf16 v[48:51], v[124:127], v[172:175], v[48:51]
	v_mfma_f32_16x16x32_bf16 v[44:47], v[140:143], v[172:175], v[44:47]
	v_mfma_f32_16x16x32_bf16 v[32:35], v[124:127], v[180:183], v[32:35]
	v_mfma_f32_16x16x32_bf16 v[28:31], v[140:143], v[180:183], v[28:31]
	v_mfma_f32_16x16x32_bf16 v[16:19], v[124:127], v[196:199], v[16:19]
	v_mfma_f32_16x16x32_bf16 v[12:15], v[140:143], v[196:199], v[12:15]
	v_mfma_f32_16x16x32_bf16 v[64:67], v[128:131], v[168:171], v[64:67]
	v_mfma_f32_16x16x32_bf16 v[60:63], v[144:147], v[168:171], v[60:63]
	v_mfma_f32_16x16x32_bf16 v[48:51], v[128:131], v[176:179], v[48:51]
	v_mfma_f32_16x16x32_bf16 v[44:47], v[144:147], v[176:179], v[44:47]
	v_mfma_f32_16x16x32_bf16 v[32:35], v[128:131], v[184:187], v[32:35]
	v_mfma_f32_16x16x32_bf16 v[28:31], v[144:147], v[184:187], v[28:31]
	v_mfma_f32_16x16x32_bf16 v[16:19], v[128:131], v[200:203], v[16:19]
	v_mfma_f32_16x16x32_bf16 v[12:15], v[144:147], v[200:203], v[12:15]
	s_setprio 0
	s_setprio 1
	v_mfma_f32_16x16x32_bf16 v[56:59], v[148:151], v[164:167], v[56:59]
	v_mfma_f32_16x16x32_bf16 v[52:55], v[156:159], v[164:167], v[52:55]
	v_mfma_f32_16x16x32_bf16 v[40:43], v[148:151], v[172:175], v[40:43]
	v_mfma_f32_16x16x32_bf16 v[36:39], v[156:159], v[172:175], v[36:39]
	v_mfma_f32_16x16x32_bf16 v[24:27], v[148:151], v[180:183], v[24:27]
	v_mfma_f32_16x16x32_bf16 v[20:23], v[156:159], v[180:183], v[20:23]
	v_mfma_f32_16x16x32_bf16 v[8:11], v[148:151], v[196:199], v[8:11]
	v_mfma_f32_16x16x32_bf16 v[4:7], v[156:159], v[196:199], v[4:7]
	v_mfma_f32_16x16x32_bf16 v[56:59], v[152:155], v[168:171], v[56:59]
	v_mfma_f32_16x16x32_bf16 v[52:55], v[160:163], v[168:171], v[52:55]
	v_mfma_f32_16x16x32_bf16 v[40:43], v[152:155], v[176:179], v[40:43]
	v_mfma_f32_16x16x32_bf16 v[36:39], v[160:163], v[176:179], v[36:39]
	v_mfma_f32_16x16x32_bf16 v[24:27], v[152:155], v[184:187], v[24:27]
	v_mfma_f32_16x16x32_bf16 v[20:23], v[160:163], v[184:187], v[20:23]
	v_mfma_f32_16x16x32_bf16 v[8:11], v[152:155], v[200:203], v[8:11]
	v_mfma_f32_16x16x32_bf16 v[4:7], v[160:163], v[200:203], v[4:7]
	s_setprio 0
	s_barrier
	s_add_i32 s48, s48, 2
	s_add_u32 s40, s40, 0x100
	s_addc_u32 s41, s41, 0
	s_cmpk_gt_u32 s48, 0x55
	s_mov_b64 s[16:17], s[18:19]
	s_cbranch_scc0 .LBB0_301
	s_and_b64 vcc, exec, s[10:11]
	s_cbranch_vccz .LBB0_304
	s_barrier

.LBB0_347:
	s_sleep 2
	s_add_u32 s16, s14, 0x100
	s_addc_u32 s17, s15, 0
	s_add_i32 s44, 0, 0x10000
	s_cmpk_eq_i32 s43, 0x54
	s_cselect_b32 s21, s11, s17
	s_cselect_b32 s20, s10, s16
	s_cselect_b32 s19, s13, s39
	s_cselect_b32 s18, s12, s38
	s_add_i32 s45, 0, 0x14000
	v_add_u32_e32 v144, s44, v236
	v_add_u32_e32 v160, s45, v236
	ds_read_b128 v[132:135], v144
	ds_read_b128 v[136:139], v144 offset:1024
	ds_read_b128 v[140:143], v144 offset:2048
	ds_read_b128 v[144:147], v144 offset:3072
	ds_read_b128 v[148:151], v160
	ds_read_b128 v[152:155], v160 offset:1024
	ds_read_b128 v[156:159], v160 offset:2048
	ds_read_b128 v[160:163], v160 offset:3072
	v_lshl_add_u64 v[204:205], s[14:15], 0, v[200:201]
	s_add_i32 m0, s23, 0xc000
	ds_read_b128 v[164:167], v238
	ds_read_b128 v[168:171], v238 offset:1024
	ds_read_b128 v[172:175], v238 offset:2048
	ds_read_b128 v[176:179], v238 offset:3072
	ds_read_b128 v[180:183], v238 offset:4096
	ds_read_b128 v[184:187], v238 offset:5120
	ds_read_b128 v[188:191], v238 offset:6144
	ds_read_b128 v[192:195], v238 offset:7168
	global_load_lds_dwordx4 v[204:205], off
	v_lshl_add_u64 v[204:205], s[14:15], 0, v[202:203]
	s_add_i32 m0, s23, 0xe000
	s_nop 0
	global_load_lds_dwordx4 v[204:205], off
	s_waitcnt vmcnt(8)
	s_waitcnt lgkmcnt(0)
	s_barrier
	s_setprio 1
	s_waitcnt lgkmcnt(0)
	v_mfma_f32_16x16x32_bf16 v[128:131], v[132:135], v[164:167], v[128:131]
	v_mfma_f32_16x16x32_bf16 v[124:127], v[140:143], v[164:167], v[124:127]
	v_mfma_f32_16x16x32_bf16 v[116:119], v[132:135], v[172:175], v[116:119]
	v_mfma_f32_16x16x32_bf16 v[108:111], v[140:143], v[172:175], v[108:111]
	v_mfma_f32_16x16x32_bf16 v[100:103], v[132:135], v[180:183], v[100:103]
	v_mfma_f32_16x16x32_bf16 v[92:95], v[140:143], v[180:183], v[92:95]
	v_mfma_f32_16x16x32_bf16 v[84:87], v[132:135], v[188:191], v[84:87]
	v_mfma_f32_16x16x32_bf16 v[76:79], v[140:143], v[188:191], v[76:79]
	v_mfma_f32_16x16x32_bf16 v[128:131], v[136:139], v[168:171], v[128:131]
	v_mfma_f32_16x16x32_bf16 v[124:127], v[144:147], v[168:171], v[124:127]
	v_mfma_f32_16x16x32_bf16 v[116:119], v[136:139], v[176:179], v[116:119]
	v_mfma_f32_16x16x32_bf16 v[108:111], v[144:147], v[176:179], v[108:111]
	v_mfma_f32_16x16x32_bf16 v[100:103], v[136:139], v[184:187], v[100:103]
	v_mfma_f32_16x16x32_bf16 v[92:95], v[144:147], v[184:187], v[92:95]
	v_mfma_f32_16x16x32_bf16 v[84:87], v[136:139], v[192:195], v[84:87]
	v_mfma_f32_16x16x32_bf16 v[76:79], v[144:147], v[192:195], v[76:79]
	s_setprio 0
	s_setprio 1
	v_mfma_f32_16x16x32_bf16 v[120:123], v[148:151], v[164:167], v[120:123]
	v_mfma_f32_16x16x32_bf16 v[112:115], v[156:159], v[164:167], v[112:115]
	v_mfma_f32_16x16x32_bf16 v[104:107], v[148:151], v[172:175], v[104:107]
	v_mfma_f32_16x16x32_bf16 v[96:99], v[156:159], v[172:175], v[96:99]
	v_mfma_f32_16x16x32_bf16 v[88:91], v[148:151], v[180:183], v[88:91]
	v_mfma_f32_16x16x32_bf16 v[80:83], v[156:159], v[180:183], v[80:83]
	v_mfma_f32_16x16x32_bf16 v[72:75], v[148:151], v[188:191], v[72:75]
	v_mfma_f32_16x16x32_bf16 v[68:71], v[156:159], v[188:191], v[68:71]
	v_mfma_f32_16x16x32_bf16 v[120:123], v[152:155], v[168:171], v[120:123]
	v_mfma_f32_16x16x32_bf16 v[112:115], v[160:163], v[168:171], v[112:115]
	v_mfma_f32_16x16x32_bf16 v[104:107], v[152:155], v[176:179], v[104:107]
	v_mfma_f32_16x16x32_bf16 v[96:99], v[160:163], v[176:179], v[96:99]
	v_mfma_f32_16x16x32_bf16 v[88:91], v[152:155], v[184:187], v[88:91]
	v_mfma_f32_16x16x32_bf16 v[80:83], v[160:163], v[184:187], v[80:83]
	v_mfma_f32_16x16x32_bf16 v[72:75], v[152:155], v[192:195], v[72:75]
	v_mfma_f32_16x16x32_bf16 v[68:71], v[160:163], v[192:195], v[68:71]
	s_setprio 0
	s_barrier
	s_sleep 2
	s_add_i32 s14, s44, s22
	v_lshl_add_u64 v[204:205], s[18:19], 0, v[2:3]
	s_mov_b32 m0, s14
	ds_read_b128 v[164:167], v238 offset:16384
	ds_read_b128 v[168:171], v238 offset:17408
	ds_read_b128 v[172:175], v238 offset:18432
	ds_read_b128 v[176:179], v238 offset:19456
	ds_read_b128 v[180:183], v238 offset:20480
	ds_read_b128 v[184:187], v238 offset:21504
	ds_read_b128 v[188:191], v238 offset:22528
	ds_read_b128 v[192:195], v238 offset:23552
	global_load_lds_dwordx4 v[204:205], off
	s_add_i32 m0, s14, 0x2000
	s_add_u32 s14, s18, 0x160000
	v_lshl_add_u64 v[206:207], s[18:19], 0, v[198:199]
	s_addc_u32 s15, s19, 0
	s_add_i32 s44, s45, s22
	global_load_lds_dwordx4 v[206:207], off
	v_lshl_add_u64 v[208:209], s[14:15], 0, v[2:3]
	s_mov_b32 m0, s44
	v_lshl_add_u64 v[210:211], s[20:21], 0, v[196:197]
	global_load_lds_dwordx4 v[208:209], off
	v_lshl_add_u64 v[208:209], s[14:15], 0, v[198:199]
	s_add_i32 m0, s44, 0x2000
	s_nop 0
	global_load_lds_dwordx4 v[208:209], off
	v_lshl_add_u64 v[208:209], s[20:21], 0, v[0:1]
	s_mov_b32 m0, s23
	s_nop 0
	global_load_lds_dwordx4 v[208:209], off
	s_mov_b32 m0, s28
	s_nop 0
	global_load_lds_dwordx4 v[210:211], off
	s_waitcnt vmcnt(8)
	s_waitcnt lgkmcnt(0)
	s_barrier
	s_setprio 1
	s_waitcnt lgkmcnt(0)
	v_mfma_f32_16x16x32_bf16 v[64:67], v[132:135], v[164:167], v[64:67]
	v_mfma_f32_16x16x32_bf16 v[60:63], v[140:143], v[164:167], v[60:63]
	v_mfma_f32_16x16x32_bf16 v[52:55], v[132:135], v[172:175], v[52:55]
	v_mfma_f32_16x16x32_bf16 v[44:47], v[140:143], v[172:175], v[44:47]
	v_mfma_f32_16x16x32_bf16 v[36:39], v[132:135], v[180:183], v[36:39]
	v_mfma_f32_16x16x32_bf16 v[28:31], v[140:143], v[180:183], v[28:31]
	v_mfma_f32_16x16x32_bf16 v[20:23], v[132:135], v[188:191], v[20:23]
	v_mfma_f32_16x16x32_bf16 v[12:15], v[140:143], v[188:191], v[12:15]
	v_mfma_f32_16x16x32_bf16 v[64:67], v[136:139], v[168:171], v[64:67]
	v_mfma_f32_16x16x32_bf16 v[60:63], v[144:147], v[168:171], v[60:63]
	v_mfma_f32_16x16x32_bf16 v[52:55], v[136:139], v[176:179], v[52:55]
	v_mfma_f32_16x16x32_bf16 v[44:47], v[144:147], v[176:179], v[44:47]
	v_mfma_f32_16x16x32_bf16 v[36:39], v[136:139], v[184:187], v[36:39]
	v_mfma_f32_16x16x32_bf16 v[28:31], v[144:147], v[184:187], v[28:31]
	v_mfma_f32_16x16x32_bf16 v[20:23], v[136:139], v[192:195], v[20:23]
	v_mfma_f32_16x16x32_bf16 v[12:15], v[144:147], v[192:195], v[12:15]
	s_setprio 0
	s_setprio 1
	v_mfma_f32_16x16x32_bf16 v[56:59], v[148:151], v[164:167], v[56:59]
	v_mfma_f32_16x16x32_bf16 v[48:51], v[156:159], v[164:167], v[48:51]
	v_mfma_f32_16x16x32_bf16 v[40:43], v[148:151], v[172:175], v[40:43]
	v_mfma_f32_16x16x32_bf16 v[32:35], v[156:159], v[172:175], v[32:35]
	v_mfma_f32_16x16x32_bf16 v[24:27], v[148:151], v[180:183], v[24:27]
	v_mfma_f32_16x16x32_bf16 v[16:19], v[156:159], v[180:183], v[16:19]
	v_mfma_f32_16x16x32_bf16 v[8:11], v[148:151], v[188:191], v[8:11]
	v_mfma_f32_16x16x32_bf16 v[4:7], v[156:159], v[188:191], v[4:7]
	v_mfma_f32_16x16x32_bf16 v[56:59], v[152:155], v[168:171], v[56:59]
	v_mfma_f32_16x16x32_bf16 v[48:51], v[160:163], v[168:171], v[48:51]
	v_mfma_f32_16x16x32_bf16 v[40:43], v[152:155], v[176:179], v[40:43]
	v_mfma_f32_16x16x32_bf16 v[32:35], v[160:163], v[176:179], v[32:35]
	v_mfma_f32_16x16x32_bf16 v[24:27], v[152:155], v[184:187], v[24:27]
	v_mfma_f32_16x16x32_bf16 v[16:19], v[160:163], v[184:187], v[16:19]
	v_mfma_f32_16x16x32_bf16 v[8:11], v[152:155], v[192:195], v[8:11]
	v_mfma_f32_16x16x32_bf16 v[4:7], v[160:163], v[192:195], v[4:7]
	s_setprio 0
	s_barrier
	s_sleep 2
	s_add_i32 s44, 0, 0x18000
	s_add_i32 s45, 0, 0x1c000
	v_add_u32_e32 v144, s44, v236
	v_add_u32_e32 v160, s45, v236
	ds_read_b128 v[132:135], v144
	ds_read_b128 v[136:139], v144 offset:1024
	ds_read_b128 v[140:143], v144 offset:2048
	ds_read_b128 v[144:147], v144 offset:3072
	ds_read_b128 v[148:151], v160
	ds_read_b128 v[152:155], v160 offset:1024
	ds_read_b128 v[156:159], v160 offset:2048
	ds_read_b128 v[160:163], v160 offset:3072
	s_add_u32 s14, s20, 0x160000
	s_addc_u32 s15, s21, 0
	s_mov_b32 m0, s29
	v_lshl_add_u64 v[212:213], s[14:15], 0, v[0:1]
	ds_read_b128 v[164:167], v238 offset:32768
	ds_read_b128 v[168:171], v238 offset:33792
	ds_read_b128 v[172:175], v238 offset:34816
	ds_read_b128 v[176:179], v238 offset:35840
	ds_read_b128 v[180:183], v238 offset:36864
	ds_read_b128 v[184:187], v238 offset:37888
	ds_read_b128 v[188:191], v238 offset:38912
	ds_read_b128 v[192:195], v238 offset:39936
	global_load_lds_dwordx4 v[212:213], off
	v_lshl_add_u64 v[212:213], s[14:15], 0, v[196:197]
	s_mov_b32 m0, s30
	s_nop 0
	global_load_lds_dwordx4 v[212:213], off
	s_waitcnt vmcnt(8)
	s_waitcnt lgkmcnt(0)
	s_barrier
	s_setprio 1
	s_waitcnt lgkmcnt(0)
	v_mfma_f32_16x16x32_bf16 v[128:131], v[132:135], v[164:167], v[128:131]
	v_mfma_f32_16x16x32_bf16 v[124:127], v[140:143], v[164:167], v[124:127]
	v_mfma_f32_16x16x32_bf16 v[116:119], v[132:135], v[172:175], v[116:119]
	v_mfma_f32_16x16x32_bf16 v[108:111], v[140:143], v[172:175], v[108:111]
	v_mfma_f32_16x16x32_bf16 v[100:103], v[132:135], v[180:183], v[100:103]
	v_mfma_f32_16x16x32_bf16 v[92:95], v[140:143], v[180:183], v[92:95]
	v_mfma_f32_16x16x32_bf16 v[84:87], v[132:135], v[188:191], v[84:87]
	v_mfma_f32_16x16x32_bf16 v[76:79], v[140:143], v[188:191], v[76:79]
	v_mfma_f32_16x16x32_bf16 v[128:131], v[136:139], v[168:171], v[128:131]
	v_mfma_f32_16x16x32_bf16 v[124:127], v[144:147], v[168:171], v[124:127]
	v_mfma_f32_16x16x32_bf16 v[116:119], v[136:139], v[176:179], v[116:119]
	v_mfma_f32_16x16x32_bf16 v[108:111], v[144:147], v[176:179], v[108:111]
	v_mfma_f32_16x16x32_bf16 v[100:103], v[136:139], v[184:187], v[100:103]
	v_mfma_f32_16x16x32_bf16 v[92:95], v[144:147], v[184:187], v[92:95]
	v_mfma_f32_16x16x32_bf16 v[84:87], v[136:139], v[192:195], v[84:87]
	v_mfma_f32_16x16x32_bf16 v[76:79], v[144:147], v[192:195], v[76:79]
	s_setprio 0
	s_setprio 1
	v_mfma_f32_16x16x32_bf16 v[120:123], v[148:151], v[164:167], v[120:123]
	v_mfma_f32_16x16x32_bf16 v[112:115], v[156:159], v[164:167], v[112:115]
	v_mfma_f32_16x16x32_bf16 v[104:107], v[148:151], v[172:175], v[104:107]
	v_mfma_f32_16x16x32_bf16 v[96:99], v[156:159], v[172:175], v[96:99]
	v_mfma_f32_16x16x32_bf16 v[88:91], v[148:151], v[180:183], v[88:91]
	v_mfma_f32_16x16x32_bf16 v[80:83], v[156:159], v[180:183], v[80:83]
	v_mfma_f32_16x16x32_bf16 v[72:75], v[148:151], v[188:191], v[72:75]
	v_mfma_f32_16x16x32_bf16 v[68:71], v[156:159], v[188:191], v[68:71]
	v_mfma_f32_16x16x32_bf16 v[120:123], v[152:155], v[168:171], v[120:123]
	v_mfma_f32_16x16x32_bf16 v[112:115], v[160:163], v[168:171], v[112:115]
	v_mfma_f32_16x16x32_bf16 v[104:107], v[152:155], v[176:179], v[104:107]
	v_mfma_f32_16x16x32_bf16 v[96:99], v[160:163], v[176:179], v[96:99]
	v_mfma_f32_16x16x32_bf16 v[88:91], v[152:155], v[184:187], v[88:91]
	v_mfma_f32_16x16x32_bf16 v[80:83], v[160:163], v[184:187], v[80:83]
	v_mfma_f32_16x16x32_bf16 v[72:75], v[152:155], v[192:195], v[72:75]
	v_mfma_f32_16x16x32_bf16 v[68:71], v[160:163], v[192:195], v[68:71]
	s_setprio 0
	s_barrier
	s_sleep 2
	s_add_i32 s14, s44, s22
	v_lshl_add_u64 v[204:205], v[204:205], 0, s[66:67]
	s_mov_b32 m0, s14
	ds_read_b128 v[164:167], v238 offset:49152
	ds_read_b128 v[168:171], v238 offset:50176
	ds_read_b128 v[172:175], v238 offset:51200
	ds_read_b128 v[176:179], v238 offset:52224
	ds_read_b128 v[180:183], v238 offset:53248
	ds_read_b128 v[184:187], v238 offset:54272
	ds_read_b128 v[188:191], v238 offset:55296
	ds_read_b128 v[192:195], v238 offset:56320
	global_load_lds_dwordx4 v[204:205], off
	s_add_i32 m0, s14, 0x2000
	s_add_u32 s14, s18, 0x160080
	v_lshl_add_u64 v[204:205], v[206:207], 0, s[66:67]
	s_addc_u32 s15, s19, 0
	s_add_i32 s18, s45, s22
	global_load_lds_dwordx4 v[204:205], off
	v_lshl_add_u64 v[204:205], s[14:15], 0, v[2:3]
	s_mov_b32 m0, s18
	s_nop 0
	global_load_lds_dwordx4 v[204:205], off
	v_lshl_add_u64 v[204:205], s[14:15], 0, v[198:199]
	s_add_i32 m0, s18, 0x2000
	s_nop 0
	global_load_lds_dwordx4 v[204:205], off
	v_lshl_add_u64 v[204:205], v[208:209], 0, s[66:67]
	s_mov_b32 m0, s31
	s_nop 0
	global_load_lds_dwordx4 v[204:205], off
	v_lshl_add_u64 v[204:205], v[210:211], 0, s[66:67]
	s_mov_b32 m0, s34
	s_nop 0
	global_load_lds_dwordx4 v[204:205], off
	s_waitcnt vmcnt(8)
	s_waitcnt lgkmcnt(0)
	s_barrier
	s_setprio 1
	s_waitcnt lgkmcnt(0)
	v_mfma_f32_16x16x32_bf16 v[64:67], v[132:135], v[164:167], v[64:67]
	v_mfma_f32_16x16x32_bf16 v[60:63], v[140:143], v[164:167], v[60:63]
	v_mfma_f32_16x16x32_bf16 v[52:55], v[132:135], v[172:175], v[52:55]
	v_mfma_f32_16x16x32_bf16 v[44:47], v[140:143], v[172:175], v[44:47]
	v_mfma_f32_16x16x32_bf16 v[36:39], v[132:135], v[180:183], v[36:39]
	v_mfma_f32_16x16x32_bf16 v[28:31], v[140:143], v[180:183], v[28:31]
	v_mfma_f32_16x16x32_bf16 v[20:23], v[132:135], v[188:191], v[20:23]
	v_mfma_f32_16x16x32_bf16 v[12:15], v[140:143], v[188:191], v[12:15]
	v_mfma_f32_16x16x32_bf16 v[64:67], v[136:139], v[168:171], v[64:67]
	v_mfma_f32_16x16x32_bf16 v[60:63], v[144:147], v[168:171], v[60:63]
	v_mfma_f32_16x16x32_bf16 v[52:55], v[136:139], v[176:179], v[52:55]
	v_mfma_f32_16x16x32_bf16 v[44:47], v[144:147], v[176:179], v[44:47]
	v_mfma_f32_16x16x32_bf16 v[36:39], v[136:139], v[184:187], v[36:39]
	v_mfma_f32_16x16x32_bf16 v[28:31], v[144:147], v[184:187], v[28:31]
	v_mfma_f32_16x16x32_bf16 v[20:23], v[136:139], v[192:195], v[20:23]
	v_mfma_f32_16x16x32_bf16 v[12:15], v[144:147], v[192:195], v[12:15]
	s_setprio 0
	s_setprio 1
	v_mfma_f32_16x16x32_bf16 v[56:59], v[148:151], v[164:167], v[56:59]
	v_mfma_f32_16x16x32_bf16 v[48:51], v[156:159], v[164:167], v[48:51]
	v_mfma_f32_16x16x32_bf16 v[40:43], v[148:151], v[172:175], v[40:43]
	v_mfma_f32_16x16x32_bf16 v[32:35], v[156:159], v[172:175], v[32:35]
	v_mfma_f32_16x16x32_bf16 v[24:27], v[148:151], v[180:183], v[24:27]
	v_mfma_f32_16x16x32_bf16 v[16:19], v[156:159], v[180:183], v[16:19]
	v_mfma_f32_16x16x32_bf16 v[8:11], v[148:151], v[188:191], v[8:11]
	v_mfma_f32_16x16x32_bf16 v[4:7], v[156:159], v[188:191], v[4:7]
	v_mfma_f32_16x16x32_bf16 v[56:59], v[152:155], v[168:171], v[56:59]
	v_mfma_f32_16x16x32_bf16 v[48:51], v[160:163], v[168:171], v[48:51]
	v_mfma_f32_16x16x32_bf16 v[40:43], v[152:155], v[176:179], v[40:43]
	v_mfma_f32_16x16x32_bf16 v[32:35], v[160:163], v[176:179], v[32:35]
	v_mfma_f32_16x16x32_bf16 v[24:27], v[152:155], v[184:187], v[24:27]
	v_mfma_f32_16x16x32_bf16 v[16:19], v[160:163], v[184:187], v[16:19]
	v_mfma_f32_16x16x32_bf16 v[8:11], v[152:155], v[192:195], v[8:11]
	v_mfma_f32_16x16x32_bf16 v[4:7], v[160:163], v[192:195], v[4:7]
	s_setprio 0
	s_barrier
	s_add_i32 s43, s43, 2
	s_add_u32 s38, s38, 0x100
	s_addc_u32 s39, s39, 0
	s_cmpk_gt_u32 s43, 0x55
	s_mov_b64 s[14:15], s[16:17]
	s_cbranch_scc0 .LBB0_347
	s_and_b64 vcc, exec, s[6:7]
	s_cbranch_vccz .LBB0_350
	s_barrier

.LBB0_430:
	s_sleep 2
	s_add_u32 s30, s28, 0xfff80080
	s_addc_u32 s31, s29, -1
	s_add_i32 s70, 0, 0x10000
	s_cmp_eq_u32 s69, 28
	s_cselect_b32 s43, s5, s31
	s_cselect_b32 s42, s23, s30
	s_cselect_b32 s31, s21, s68
	s_cselect_b32 s30, s62, s63
	s_add_i32 s73, 0, 0x14000
	s_waitcnt lgkmcnt(0)
	v_add_u32_e32 v152, s70, v163
	v_add_u32_e32 v160, s73, v163
	ds_read_b128 v[132:135], v152
	ds_read_b128 v[136:139], v152 offset:1024
	ds_read_b128 v[148:151], v152 offset:2048
	ds_read_b128 v[152:155], v152 offset:3072
	ds_read_b128 v[156:159], v160
	ds_read_b128 v[170:173], v160 offset:1024
	ds_read_b128 v[174:177], v160 offset:2048
	ds_read_b128 v[178:181], v160 offset:3072
	v_lshl_add_u64 v[160:161], s[28:29], 0, v[144:145]
	s_add_i32 m0, s15, 0xc000
	ds_read_b128 v[182:185], v167
	ds_read_b128 v[186:189], v167 offset:1024
	ds_read_b128 v[190:193], v167 offset:2048
	ds_read_b128 v[194:197], v167 offset:3072
	ds_read_b128 v[198:201], v167 offset:4096
	ds_read_b128 v[208:211], v167 offset:5120
	ds_read_b128 v[212:215], v167 offset:6144
	ds_read_b128 v[216:219], v167 offset:7168
	global_load_lds_dwordx4 v[160:161], off
	v_lshl_add_u64 v[160:161], s[28:29], 0, v[146:147]
	s_add_i32 m0, s15, 0xe000
	s_nop 0
	global_load_lds_dwordx4 v[160:161], off
	s_waitcnt vmcnt(8)
	s_waitcnt lgkmcnt(0)
	s_barrier
	s_setprio 1
	s_waitcnt lgkmcnt(0)
	v_mfma_f32_16x16x32_bf16 v[128:131], v[132:135], v[182:185], v[128:131]
	v_mfma_f32_16x16x32_bf16 v[124:127], v[148:151], v[182:185], v[124:127]
	v_mfma_f32_16x16x32_bf16 v[120:123], v[132:135], v[190:193], v[120:123]
	v_mfma_f32_16x16x32_bf16 v[112:115], v[148:151], v[190:193], v[112:115]
	v_mfma_f32_16x16x32_bf16 v[104:107], v[132:135], v[198:201], v[104:107]
	v_mfma_f32_16x16x32_bf16 v[96:99], v[148:151], v[198:201], v[96:99]
	v_mfma_f32_16x16x32_bf16 v[88:91], v[132:135], v[212:215], v[88:91]
	v_mfma_f32_16x16x32_bf16 v[80:83], v[148:151], v[212:215], v[80:83]
	v_mfma_f32_16x16x32_bf16 v[128:131], v[136:139], v[186:189], v[128:131]
	v_mfma_f32_16x16x32_bf16 v[124:127], v[152:155], v[186:189], v[124:127]
	v_mfma_f32_16x16x32_bf16 v[120:123], v[136:139], v[194:197], v[120:123]
	v_mfma_f32_16x16x32_bf16 v[112:115], v[152:155], v[194:197], v[112:115]
	v_mfma_f32_16x16x32_bf16 v[104:107], v[136:139], v[208:211], v[104:107]
	v_mfma_f32_16x16x32_bf16 v[96:99], v[152:155], v[208:211], v[96:99]
	v_mfma_f32_16x16x32_bf16 v[88:91], v[136:139], v[216:219], v[88:91]
	v_mfma_f32_16x16x32_bf16 v[80:83], v[152:155], v[216:219], v[80:83]
	s_setprio 0
	s_setprio 1
	v_mfma_f32_16x16x32_bf16 v[116:119], v[156:159], v[182:185], v[116:119]
	v_mfma_f32_16x16x32_bf16 v[108:111], v[174:177], v[182:185], v[108:111]
	v_mfma_f32_16x16x32_bf16 v[100:103], v[156:159], v[190:193], v[100:103]
	v_mfma_f32_16x16x32_bf16 v[92:95], v[174:177], v[190:193], v[92:95]
	v_mfma_f32_16x16x32_bf16 v[84:87], v[156:159], v[198:201], v[84:87]
	v_mfma_f32_16x16x32_bf16 v[76:79], v[174:177], v[198:201], v[76:79]
	v_mfma_f32_16x16x32_bf16 v[72:75], v[156:159], v[212:215], v[72:75]
	v_mfma_f32_16x16x32_bf16 v[68:71], v[174:177], v[212:215], v[68:71]
	v_mfma_f32_16x16x32_bf16 v[116:119], v[170:173], v[186:189], v[116:119]
	v_mfma_f32_16x16x32_bf16 v[108:111], v[178:181], v[186:189], v[108:111]
	v_mfma_f32_16x16x32_bf16 v[100:103], v[170:173], v[194:197], v[100:103]
	v_mfma_f32_16x16x32_bf16 v[92:95], v[178:181], v[194:197], v[92:95]
	v_mfma_f32_16x16x32_bf16 v[84:87], v[170:173], v[208:211], v[84:87]
	v_mfma_f32_16x16x32_bf16 v[76:79], v[178:181], v[208:211], v[76:79]
	v_mfma_f32_16x16x32_bf16 v[72:75], v[170:173], v[216:219], v[72:75]
	v_mfma_f32_16x16x32_bf16 v[68:71], v[178:181], v[216:219], v[68:71]
	s_setprio 0
	s_barrier
	s_sleep 2
	s_add_i32 s70, s70, s0
	v_lshl_add_u64 v[160:161], s[30:31], 0, v[2:3]
	s_mov_b32 m0, s70
	ds_read_b128 v[182:185], v167 offset:16384
	ds_read_b128 v[186:189], v167 offset:17408
	ds_read_b128 v[190:193], v167 offset:18432
	ds_read_b128 v[194:197], v167 offset:19456
	ds_read_b128 v[198:201], v167 offset:20480
	ds_read_b128 v[208:211], v167 offset:21504
	ds_read_b128 v[212:215], v167 offset:22528
	ds_read_b128 v[216:219], v167 offset:23552
	global_load_lds_dwordx4 v[160:161], off
	s_add_i32 m0, s70, 0x2000
	s_add_u32 s70, s30, 0x80000
	v_lshl_add_u64 v[202:203], s[30:31], 0, v[142:143]
	s_addc_u32 s71, s31, 0
	s_add_i32 s73, s73, s0
	global_load_lds_dwordx4 v[202:203], off
	v_lshl_add_u64 v[204:205], s[70:71], 0, v[2:3]
	s_mov_b32 m0, s73
	v_lshl_add_u64 v[206:207], s[42:43], 0, v[140:141]
	global_load_lds_dwordx4 v[204:205], off
	v_lshl_add_u64 v[204:205], s[70:71], 0, v[142:143]
	s_add_i32 m0, s73, 0x2000
	s_nop 0
	global_load_lds_dwordx4 v[204:205], off
	v_lshl_add_u64 v[204:205], s[42:43], 0, v[0:1]
	s_mov_b32 m0, s15
	s_nop 0
	global_load_lds_dwordx4 v[204:205], off
	s_mov_b32 m0, s53
	s_nop 0
	global_load_lds_dwordx4 v[206:207], off
	s_waitcnt vmcnt(8)
	s_waitcnt lgkmcnt(0)
	s_barrier
	s_setprio 1
	s_waitcnt lgkmcnt(0)
	v_mfma_f32_16x16x32_bf16 v[64:67], v[132:135], v[182:185], v[64:67]
	v_mfma_f32_16x16x32_bf16 v[60:63], v[148:151], v[182:185], v[60:63]
	v_mfma_f32_16x16x32_bf16 v[56:59], v[132:135], v[190:193], v[56:59]
	v_mfma_f32_16x16x32_bf16 v[48:51], v[148:151], v[190:193], v[48:51]
	v_mfma_f32_16x16x32_bf16 v[40:43], v[132:135], v[198:201], v[40:43]
	v_mfma_f32_16x16x32_bf16 v[32:35], v[148:151], v[198:201], v[32:35]
	v_mfma_f32_16x16x32_bf16 v[24:27], v[132:135], v[212:215], v[24:27]
	v_mfma_f32_16x16x32_bf16 v[16:19], v[148:151], v[212:215], v[16:19]
	v_mfma_f32_16x16x32_bf16 v[64:67], v[136:139], v[186:189], v[64:67]
	v_mfma_f32_16x16x32_bf16 v[60:63], v[152:155], v[186:189], v[60:63]
	v_mfma_f32_16x16x32_bf16 v[56:59], v[136:139], v[194:197], v[56:59]
	v_mfma_f32_16x16x32_bf16 v[48:51], v[152:155], v[194:197], v[48:51]
	v_mfma_f32_16x16x32_bf16 v[40:43], v[136:139], v[208:211], v[40:43]
	v_mfma_f32_16x16x32_bf16 v[32:35], v[152:155], v[208:211], v[32:35]
	v_mfma_f32_16x16x32_bf16 v[24:27], v[136:139], v[216:219], v[24:27]
	v_mfma_f32_16x16x32_bf16 v[16:19], v[152:155], v[216:219], v[16:19]
	s_setprio 0
	s_setprio 1
	v_mfma_f32_16x16x32_bf16 v[52:55], v[156:159], v[182:185], v[52:55]
	v_mfma_f32_16x16x32_bf16 v[44:47], v[174:177], v[182:185], v[44:47]
	v_mfma_f32_16x16x32_bf16 v[36:39], v[156:159], v[190:193], v[36:39]
	v_mfma_f32_16x16x32_bf16 v[28:31], v[174:177], v[190:193], v[28:31]
	v_mfma_f32_16x16x32_bf16 v[20:23], v[156:159], v[198:201], v[20:23]
	v_mfma_f32_16x16x32_bf16 v[12:15], v[174:177], v[198:201], v[12:15]
	v_mfma_f32_16x16x32_bf16 v[8:11], v[156:159], v[212:215], v[8:11]
	v_mfma_f32_16x16x32_bf16 v[4:7], v[174:177], v[212:215], v[4:7]
	v_mfma_f32_16x16x32_bf16 v[52:55], v[170:173], v[186:189], v[52:55]
	v_mfma_f32_16x16x32_bf16 v[44:47], v[178:181], v[186:189], v[44:47]
	v_mfma_f32_16x16x32_bf16 v[36:39], v[170:173], v[194:197], v[36:39]
	v_mfma_f32_16x16x32_bf16 v[28:31], v[178:181], v[194:197], v[28:31]
	v_mfma_f32_16x16x32_bf16 v[20:23], v[170:173], v[208:211], v[20:23]
	v_mfma_f32_16x16x32_bf16 v[12:15], v[178:181], v[208:211], v[12:15]
	v_mfma_f32_16x16x32_bf16 v[8:11], v[170:173], v[216:219], v[8:11]
	v_mfma_f32_16x16x32_bf16 v[4:7], v[178:181], v[216:219], v[4:7]
	s_setprio 0
	s_barrier
	s_sleep 2
	s_add_i32 s70, 0, 0x18000
	s_add_i32 s71, 0, 0x1c000
	v_add_u32_e32 v152, s70, v163
	v_add_u32_e32 v178, s71, v163
	ds_read_b128 v[132:135], v152
	ds_read_b128 v[136:139], v152 offset:1024
	ds_read_b128 v[148:151], v152 offset:2048
	ds_read_b128 v[152:155], v152 offset:3072
	ds_read_b128 v[156:159], v178
	ds_read_b128 v[170:173], v178 offset:1024
	ds_read_b128 v[174:177], v178 offset:2048
	ds_read_b128 v[178:181], v178 offset:3072
	s_add_u32 s42, s42, 0x80000
	s_addc_u32 s43, s43, 0
	s_mov_b32 m0, s54
	v_lshl_add_u64 v[220:221], s[42:43], 0, v[0:1]
	ds_read_b128 v[182:185], v167 offset:32768
	ds_read_b128 v[186:189], v167 offset:33792
	ds_read_b128 v[190:193], v167 offset:34816
	ds_read_b128 v[194:197], v167 offset:35840
	ds_read_b128 v[198:201], v167 offset:36864
	ds_read_b128 v[208:211], v167 offset:37888
	ds_read_b128 v[212:215], v167 offset:38912
	ds_read_b128 v[216:219], v167 offset:39936
	global_load_lds_dwordx4 v[220:221], off
	v_lshl_add_u64 v[220:221], s[42:43], 0, v[140:141]
	s_mov_b32 m0, s55
	s_nop 0
	global_load_lds_dwordx4 v[220:221], off
	s_waitcnt vmcnt(8)
	s_waitcnt lgkmcnt(0)
	s_barrier
	s_setprio 1
	s_waitcnt lgkmcnt(0)
	v_mfma_f32_16x16x32_bf16 v[128:131], v[132:135], v[182:185], v[128:131]
	v_mfma_f32_16x16x32_bf16 v[124:127], v[148:151], v[182:185], v[124:127]
	v_mfma_f32_16x16x32_bf16 v[120:123], v[132:135], v[190:193], v[120:123]
	v_mfma_f32_16x16x32_bf16 v[112:115], v[148:151], v[190:193], v[112:115]
	v_mfma_f32_16x16x32_bf16 v[104:107], v[132:135], v[198:201], v[104:107]
	v_mfma_f32_16x16x32_bf16 v[96:99], v[148:151], v[198:201], v[96:99]
	v_mfma_f32_16x16x32_bf16 v[88:91], v[132:135], v[212:215], v[88:91]
	v_mfma_f32_16x16x32_bf16 v[80:83], v[148:151], v[212:215], v[80:83]
	v_mfma_f32_16x16x32_bf16 v[128:131], v[136:139], v[186:189], v[128:131]
	v_mfma_f32_16x16x32_bf16 v[124:127], v[152:155], v[186:189], v[124:127]
	v_mfma_f32_16x16x32_bf16 v[120:123], v[136:139], v[194:197], v[120:123]
	v_mfma_f32_16x16x32_bf16 v[112:115], v[152:155], v[194:197], v[112:115]
	v_mfma_f32_16x16x32_bf16 v[104:107], v[136:139], v[208:211], v[104:107]
	v_mfma_f32_16x16x32_bf16 v[96:99], v[152:155], v[208:211], v[96:99]
	v_mfma_f32_16x16x32_bf16 v[88:91], v[136:139], v[216:219], v[88:91]
	v_mfma_f32_16x16x32_bf16 v[80:83], v[152:155], v[216:219], v[80:83]
	s_setprio 0
	s_setprio 1
	v_mfma_f32_16x16x32_bf16 v[116:119], v[156:159], v[182:185], v[116:119]
	v_mfma_f32_16x16x32_bf16 v[108:111], v[174:177], v[182:185], v[108:111]
	v_mfma_f32_16x16x32_bf16 v[100:103], v[156:159], v[190:193], v[100:103]
	v_mfma_f32_16x16x32_bf16 v[92:95], v[174:177], v[190:193], v[92:95]
	v_mfma_f32_16x16x32_bf16 v[84:87], v[156:159], v[198:201], v[84:87]
	v_mfma_f32_16x16x32_bf16 v[76:79], v[174:177], v[198:201], v[76:79]
	v_mfma_f32_16x16x32_bf16 v[72:75], v[156:159], v[212:215], v[72:75]
	v_mfma_f32_16x16x32_bf16 v[68:71], v[174:177], v[212:215], v[68:71]
	v_mfma_f32_16x16x32_bf16 v[116:119], v[170:173], v[186:189], v[116:119]
	v_mfma_f32_16x16x32_bf16 v[108:111], v[178:181], v[186:189], v[108:111]
	v_mfma_f32_16x16x32_bf16 v[100:103], v[170:173], v[194:197], v[100:103]
	v_mfma_f32_16x16x32_bf16 v[92:95], v[178:181], v[194:197], v[92:95]
	v_mfma_f32_16x16x32_bf16 v[84:87], v[170:173], v[208:211], v[84:87]
	v_mfma_f32_16x16x32_bf16 v[76:79], v[178:181], v[208:211], v[76:79]
	v_mfma_f32_16x16x32_bf16 v[72:75], v[170:173], v[216:219], v[72:75]
	v_mfma_f32_16x16x32_bf16 v[68:71], v[178:181], v[216:219], v[68:71]
	s_setprio 0
	s_barrier
	s_sleep 2
	s_add_i32 s42, s70, s0
	v_lshl_add_u64 v[160:161], v[160:161], 0, s[66:67]
	s_mov_b32 m0, s42
	ds_read_b128 v[182:185], v167 offset:49152
	ds_read_b128 v[186:189], v167 offset:50176
	ds_read_b128 v[190:193], v167 offset:51200
	ds_read_b128 v[194:197], v167 offset:52224
	ds_read_b128 v[198:201], v167 offset:53248
	ds_read_b128 v[208:211], v167 offset:54272
	ds_read_b128 v[212:215], v167 offset:55296
	ds_read_b128 v[216:219], v167 offset:56320
	global_load_lds_dwordx4 v[160:161], off
	s_add_i32 m0, s42, 0x2000
	s_add_u32 s30, s30, 0x80080
	v_lshl_add_u64 v[160:161], v[202:203], 0, s[66:67]
	s_addc_u32 s31, s31, 0
	s_add_i32 s42, s71, s0
	global_load_lds_dwordx4 v[160:161], off
	v_lshl_add_u64 v[160:161], s[30:31], 0, v[2:3]
	s_mov_b32 m0, s42
	s_nop 0
	global_load_lds_dwordx4 v[160:161], off
	v_lshl_add_u64 v[160:161], s[30:31], 0, v[142:143]
	s_add_i32 m0, s42, 0x2000
	s_nop 0
	global_load_lds_dwordx4 v[160:161], off
	v_lshl_add_u64 v[160:161], v[204:205], 0, s[66:67]
	s_mov_b32 m0, s60
	s_nop 0
	global_load_lds_dwordx4 v[160:161], off
	v_lshl_add_u64 v[160:161], v[206:207], 0, s[66:67]
	s_mov_b32 m0, s64
	s_nop 0
	global_load_lds_dwordx4 v[160:161], off
	s_waitcnt vmcnt(8)
	s_waitcnt lgkmcnt(0)
	s_barrier
	s_setprio 1
	s_waitcnt lgkmcnt(0)
	v_mfma_f32_16x16x32_bf16 v[64:67], v[132:135], v[182:185], v[64:67]
	v_mfma_f32_16x16x32_bf16 v[60:63], v[148:151], v[182:185], v[60:63]
	v_mfma_f32_16x16x32_bf16 v[56:59], v[132:135], v[190:193], v[56:59]
	v_mfma_f32_16x16x32_bf16 v[48:51], v[148:151], v[190:193], v[48:51]
	v_mfma_f32_16x16x32_bf16 v[40:43], v[132:135], v[198:201], v[40:43]
	v_mfma_f32_16x16x32_bf16 v[32:35], v[148:151], v[198:201], v[32:35]
	v_mfma_f32_16x16x32_bf16 v[24:27], v[132:135], v[212:215], v[24:27]
	v_mfma_f32_16x16x32_bf16 v[16:19], v[148:151], v[212:215], v[16:19]
	v_mfma_f32_16x16x32_bf16 v[64:67], v[136:139], v[186:189], v[64:67]
	v_mfma_f32_16x16x32_bf16 v[60:63], v[152:155], v[186:189], v[60:63]
	v_mfma_f32_16x16x32_bf16 v[56:59], v[136:139], v[194:197], v[56:59]
	v_mfma_f32_16x16x32_bf16 v[48:51], v[152:155], v[194:197], v[48:51]
	v_mfma_f32_16x16x32_bf16 v[40:43], v[136:139], v[208:211], v[40:43]
	v_mfma_f32_16x16x32_bf16 v[32:35], v[152:155], v[208:211], v[32:35]
	v_mfma_f32_16x16x32_bf16 v[24:27], v[136:139], v[216:219], v[24:27]
	v_mfma_f32_16x16x32_bf16 v[16:19], v[152:155], v[216:219], v[16:19]
	s_setprio 0
	s_setprio 1
	v_mfma_f32_16x16x32_bf16 v[52:55], v[156:159], v[182:185], v[52:55]
	v_mfma_f32_16x16x32_bf16 v[44:47], v[174:177], v[182:185], v[44:47]
	v_mfma_f32_16x16x32_bf16 v[36:39], v[156:159], v[190:193], v[36:39]
	v_mfma_f32_16x16x32_bf16 v[28:31], v[174:177], v[190:193], v[28:31]
	v_mfma_f32_16x16x32_bf16 v[20:23], v[156:159], v[198:201], v[20:23]
	v_mfma_f32_16x16x32_bf16 v[12:15], v[174:177], v[198:201], v[12:15]
	v_mfma_f32_16x16x32_bf16 v[8:11], v[156:159], v[212:215], v[8:11]
	v_mfma_f32_16x16x32_bf16 v[4:7], v[174:177], v[212:215], v[4:7]
	v_mfma_f32_16x16x32_bf16 v[52:55], v[170:173], v[186:189], v[52:55]
	v_mfma_f32_16x16x32_bf16 v[44:47], v[178:181], v[186:189], v[44:47]
	v_mfma_f32_16x16x32_bf16 v[36:39], v[170:173], v[194:197], v[36:39]
	v_mfma_f32_16x16x32_bf16 v[28:31], v[178:181], v[194:197], v[28:31]
	v_mfma_f32_16x16x32_bf16 v[20:23], v[170:173], v[208:211], v[20:23]
	v_mfma_f32_16x16x32_bf16 v[12:15], v[178:181], v[208:211], v[12:15]
	v_mfma_f32_16x16x32_bf16 v[8:11], v[170:173], v[216:219], v[8:11]
	v_mfma_f32_16x16x32_bf16 v[4:7], v[178:181], v[216:219], v[4:7]
	s_setprio 0
	s_barrier
	s_add_i32 s69, s69, 2
	s_add_u32 s28, s28, 0x100
	s_addc_u32 s29, s29, 0
	s_add_u32 s63, s63, 0x100
	s_addc_u32 s68, s68, 0
	s_cmp_gt_u32 s69, 29
	s_cbranch_scc0 .LBB0_430
	s_and_b64 vcc, exec, s[8:9]
	s_cbranch_vccz .LBB0_433
	s_barrier

.LBB0_495:
	s_sleep 2
	s_add_u32 s22, s20, 0xfff80080
	s_addc_u32 s23, s21, -1
	s_add_i32 s48, 0, 0x10000
	s_cmp_eq_u32 s47, 28
	s_cselect_b32 s25, s15, s23
	s_cselect_b32 s24, s43, s22
	s_cselect_b32 s23, s11, s46
	s_cselect_b32 s22, s44, s45
	s_add_i32 s50, 0, 0x14000
	s_waitcnt lgkmcnt(0)
	v_add_u32_e32 v152, s48, v137
	v_add_u32_e32 v168, s50, v137
	ds_read_b128 v[140:143], v152
	ds_read_b128 v[144:147], v152 offset:1024
	ds_read_b128 v[148:151], v152 offset:2048
	ds_read_b128 v[152:155], v152 offset:3072
	ds_read_b128 v[156:159], v168
	ds_read_b128 v[160:163], v168 offset:1024
	ds_read_b128 v[164:167], v168 offset:2048
	ds_read_b128 v[168:171], v168 offset:3072
	v_lshl_add_u64 v[204:205], s[20:21], 0, v[132:133]
	s_add_i32 m0, s31, 0xc000
	ds_read_b128 v[172:175], v139
	ds_read_b128 v[176:179], v139 offset:1024
	ds_read_b128 v[180:183], v139 offset:2048
	ds_read_b128 v[184:187], v139 offset:3072
	ds_read_b128 v[188:191], v139 offset:4096
	ds_read_b128 v[192:195], v139 offset:5120
	ds_read_b128 v[196:199], v139 offset:6144
	ds_read_b128 v[200:203], v139 offset:7168
	global_load_lds_dwordx4 v[204:205], off
	v_lshl_add_u64 v[204:205], s[20:21], 0, v[134:135]
	s_add_i32 m0, s31, 0xe000
	s_nop 0
	global_load_lds_dwordx4 v[204:205], off
	s_waitcnt vmcnt(8)
	s_waitcnt lgkmcnt(0)
	s_barrier
	s_setprio 1
	s_waitcnt lgkmcnt(0)
	v_mfma_f32_16x16x32_bf16 v[128:131], v[140:143], v[172:175], v[128:131]
	v_mfma_f32_16x16x32_bf16 v[124:127], v[148:151], v[172:175], v[124:127]
	v_mfma_f32_16x16x32_bf16 v[120:123], v[140:143], v[180:183], v[120:123]
	v_mfma_f32_16x16x32_bf16 v[116:119], v[148:151], v[180:183], v[116:119]
	v_mfma_f32_16x16x32_bf16 v[108:111], v[140:143], v[188:191], v[108:111]
	v_mfma_f32_16x16x32_bf16 v[100:103], v[148:151], v[188:191], v[100:103]
	v_mfma_f32_16x16x32_bf16 v[92:95], v[140:143], v[196:199], v[92:95]
	v_mfma_f32_16x16x32_bf16 v[84:87], v[148:151], v[196:199], v[84:87]
	v_mfma_f32_16x16x32_bf16 v[128:131], v[144:147], v[176:179], v[128:131]
	v_mfma_f32_16x16x32_bf16 v[124:127], v[152:155], v[176:179], v[124:127]
	v_mfma_f32_16x16x32_bf16 v[120:123], v[144:147], v[184:187], v[120:123]
	v_mfma_f32_16x16x32_bf16 v[116:119], v[152:155], v[184:187], v[116:119]
	v_mfma_f32_16x16x32_bf16 v[108:111], v[144:147], v[192:195], v[108:111]
	v_mfma_f32_16x16x32_bf16 v[100:103], v[152:155], v[192:195], v[100:103]
	v_mfma_f32_16x16x32_bf16 v[92:95], v[144:147], v[200:203], v[92:95]
	v_mfma_f32_16x16x32_bf16 v[84:87], v[152:155], v[200:203], v[84:87]
	s_setprio 0
	s_setprio 1
	v_mfma_f32_16x16x32_bf16 v[112:115], v[156:159], v[172:175], v[112:115]
	v_mfma_f32_16x16x32_bf16 v[104:107], v[164:167], v[172:175], v[104:107]
	v_mfma_f32_16x16x32_bf16 v[96:99], v[156:159], v[180:183], v[96:99]
	v_mfma_f32_16x16x32_bf16 v[88:91], v[164:167], v[180:183], v[88:91]
	v_mfma_f32_16x16x32_bf16 v[80:83], v[156:159], v[188:191], v[80:83]
	v_mfma_f32_16x16x32_bf16 v[76:79], v[164:167], v[188:191], v[76:79]
	v_mfma_f32_16x16x32_bf16 v[72:75], v[156:159], v[196:199], v[72:75]
	v_mfma_f32_16x16x32_bf16 v[68:71], v[164:167], v[196:199], v[68:71]
	v_mfma_f32_16x16x32_bf16 v[112:115], v[160:163], v[176:179], v[112:115]
	v_mfma_f32_16x16x32_bf16 v[104:107], v[168:171], v[176:179], v[104:107]
	v_mfma_f32_16x16x32_bf16 v[96:99], v[160:163], v[184:187], v[96:99]
	v_mfma_f32_16x16x32_bf16 v[88:91], v[168:171], v[184:187], v[88:91]
	v_mfma_f32_16x16x32_bf16 v[80:83], v[160:163], v[192:195], v[80:83]
	v_mfma_f32_16x16x32_bf16 v[76:79], v[168:171], v[192:195], v[76:79]
	v_mfma_f32_16x16x32_bf16 v[72:75], v[160:163], v[200:203], v[72:75]
	v_mfma_f32_16x16x32_bf16 v[68:71], v[168:171], v[200:203], v[68:71]
	s_setprio 0
	s_barrier
	s_sleep 2
	s_add_i32 s48, s48, s0
	v_lshl_add_u64 v[204:205], s[22:23], 0, v[2:3]
	s_mov_b32 m0, s48
	ds_read_b128 v[172:175], v139 offset:16384
	ds_read_b128 v[176:179], v139 offset:17408
	ds_read_b128 v[180:183], v139 offset:18432
	ds_read_b128 v[184:187], v139 offset:19456
	ds_read_b128 v[188:191], v139 offset:20480
	ds_read_b128 v[192:195], v139 offset:21504
	ds_read_b128 v[196:199], v139 offset:22528
	ds_read_b128 v[200:203], v139 offset:23552
	global_load_lds_dwordx4 v[204:205], off
	s_add_i32 m0, s48, 0x2000
	s_add_u32 s48, s22, 0x80000
	v_lshl_add_u64 v[206:207], s[22:23], 0, v[0:1]
	s_addc_u32 s49, s23, 0
	s_add_i32 s50, s50, s0
	global_load_lds_dwordx4 v[206:207], off
	v_lshl_add_u64 v[208:209], s[48:49], 0, v[2:3]
	s_mov_b32 m0, s50
	v_lshl_add_u64 v[210:211], s[24:25], 0, v[0:1]
	global_load_lds_dwordx4 v[208:209], off
	v_lshl_add_u64 v[208:209], s[48:49], 0, v[0:1]
	s_add_i32 m0, s50, 0x2000
	s_nop 0
	global_load_lds_dwordx4 v[208:209], off
	v_lshl_add_u64 v[208:209], s[24:25], 0, v[2:3]
	s_mov_b32 m0, s31
	s_nop 0
	global_load_lds_dwordx4 v[208:209], off
	s_mov_b32 m0, s40
	s_nop 0
	global_load_lds_dwordx4 v[210:211], off
	s_waitcnt vmcnt(8)
	s_waitcnt lgkmcnt(0)
	s_barrier
	s_setprio 1
	s_waitcnt lgkmcnt(0)
	v_mfma_f32_16x16x32_bf16 v[64:67], v[140:143], v[172:175], v[64:67]
	v_mfma_f32_16x16x32_bf16 v[60:63], v[148:151], v[172:175], v[60:63]
	v_mfma_f32_16x16x32_bf16 v[56:59], v[140:143], v[180:183], v[56:59]
	v_mfma_f32_16x16x32_bf16 v[52:55], v[148:151], v[180:183], v[52:55]
	v_mfma_f32_16x16x32_bf16 v[40:43], v[140:143], v[188:191], v[40:43]
	v_mfma_f32_16x16x32_bf16 v[36:39], v[148:151], v[188:191], v[36:39]
	v_mfma_f32_16x16x32_bf16 v[24:27], v[140:143], v[196:199], v[24:27]
	v_mfma_f32_16x16x32_bf16 v[20:23], v[148:151], v[196:199], v[20:23]
	v_mfma_f32_16x16x32_bf16 v[64:67], v[144:147], v[176:179], v[64:67]
	v_mfma_f32_16x16x32_bf16 v[60:63], v[152:155], v[176:179], v[60:63]
	v_mfma_f32_16x16x32_bf16 v[56:59], v[144:147], v[184:187], v[56:59]
	v_mfma_f32_16x16x32_bf16 v[52:55], v[152:155], v[184:187], v[52:55]
	v_mfma_f32_16x16x32_bf16 v[40:43], v[144:147], v[192:195], v[40:43]
	v_mfma_f32_16x16x32_bf16 v[36:39], v[152:155], v[192:195], v[36:39]
	v_mfma_f32_16x16x32_bf16 v[24:27], v[144:147], v[200:203], v[24:27]
	v_mfma_f32_16x16x32_bf16 v[20:23], v[152:155], v[200:203], v[20:23]
	s_setprio 0
	s_setprio 1
	v_mfma_f32_16x16x32_bf16 v[48:51], v[156:159], v[172:175], v[48:51]
	v_mfma_f32_16x16x32_bf16 v[44:47], v[164:167], v[172:175], v[44:47]
	v_mfma_f32_16x16x32_bf16 v[32:35], v[156:159], v[180:183], v[32:35]
	v_mfma_f32_16x16x32_bf16 v[28:31], v[164:167], v[180:183], v[28:31]
	v_mfma_f32_16x16x32_bf16 v[16:19], v[156:159], v[188:191], v[16:19]
	v_mfma_f32_16x16x32_bf16 v[12:15], v[164:167], v[188:191], v[12:15]
	v_mfma_f32_16x16x32_bf16 v[8:11], v[156:159], v[196:199], v[8:11]
	v_mfma_f32_16x16x32_bf16 v[4:7], v[164:167], v[196:199], v[4:7]
	v_mfma_f32_16x16x32_bf16 v[48:51], v[160:163], v[176:179], v[48:51]
	v_mfma_f32_16x16x32_bf16 v[44:47], v[168:171], v[176:179], v[44:47]
	v_mfma_f32_16x16x32_bf16 v[32:35], v[160:163], v[184:187], v[32:35]
	v_mfma_f32_16x16x32_bf16 v[28:31], v[168:171], v[184:187], v[28:31]
	v_mfma_f32_16x16x32_bf16 v[16:19], v[160:163], v[192:195], v[16:19]
	v_mfma_f32_16x16x32_bf16 v[12:15], v[168:171], v[192:195], v[12:15]
	v_mfma_f32_16x16x32_bf16 v[8:11], v[160:163], v[200:203], v[8:11]
	v_mfma_f32_16x16x32_bf16 v[4:7], v[168:171], v[200:203], v[4:7]
	s_setprio 0
	s_barrier
	s_sleep 2
	s_add_i32 s48, 0, 0x18000
	s_add_i32 s49, 0, 0x1c000
	v_add_u32_e32 v152, s48, v137
	v_add_u32_e32 v168, s49, v137
	ds_read_b128 v[140:143], v152
	ds_read_b128 v[144:147], v152 offset:1024
	ds_read_b128 v[148:151], v152 offset:2048
	ds_read_b128 v[152:155], v152 offset:3072
	ds_read_b128 v[156:159], v168
	ds_read_b128 v[160:163], v168 offset:1024
	ds_read_b128 v[164:167], v168 offset:2048
	ds_read_b128 v[168:171], v168 offset:3072
	s_add_u32 s24, s24, 0x80000
	s_addc_u32 s25, s25, 0
	s_mov_b32 m0, s41
	v_lshl_add_u64 v[212:213], s[24:25], 0, v[2:3]
	ds_read_b128 v[172:175], v139 offset:32768
	ds_read_b128 v[176:179], v139 offset:33792
	ds_read_b128 v[180:183], v139 offset:34816
	ds_read_b128 v[184:187], v139 offset:35840
	ds_read_b128 v[188:191], v139 offset:36864
	ds_read_b128 v[192:195], v139 offset:37888
	ds_read_b128 v[196:199], v139 offset:38912
	ds_read_b128 v[200:203], v139 offset:39936
	global_load_lds_dwordx4 v[212:213], off
	v_lshl_add_u64 v[212:213], s[24:25], 0, v[0:1]
	s_mov_b32 m0, s42
	s_nop 0
	global_load_lds_dwordx4 v[212:213], off
	s_waitcnt vmcnt(8)
	s_waitcnt lgkmcnt(0)
	s_barrier
	s_setprio 1
	s_waitcnt lgkmcnt(0)
	v_mfma_f32_16x16x32_bf16 v[128:131], v[140:143], v[172:175], v[128:131]
	v_mfma_f32_16x16x32_bf16 v[124:127], v[148:151], v[172:175], v[124:127]
	v_mfma_f32_16x16x32_bf16 v[120:123], v[140:143], v[180:183], v[120:123]
	v_mfma_f32_16x16x32_bf16 v[116:119], v[148:151], v[180:183], v[116:119]
	v_mfma_f32_16x16x32_bf16 v[108:111], v[140:143], v[188:191], v[108:111]
	v_mfma_f32_16x16x32_bf16 v[100:103], v[148:151], v[188:191], v[100:103]
	v_mfma_f32_16x16x32_bf16 v[92:95], v[140:143], v[196:199], v[92:95]
	v_mfma_f32_16x16x32_bf16 v[84:87], v[148:151], v[196:199], v[84:87]
	v_mfma_f32_16x16x32_bf16 v[128:131], v[144:147], v[176:179], v[128:131]
	v_mfma_f32_16x16x32_bf16 v[124:127], v[152:155], v[176:179], v[124:127]
	v_mfma_f32_16x16x32_bf16 v[120:123], v[144:147], v[184:187], v[120:123]
	v_mfma_f32_16x16x32_bf16 v[116:119], v[152:155], v[184:187], v[116:119]
	v_mfma_f32_16x16x32_bf16 v[108:111], v[144:147], v[192:195], v[108:111]
	v_mfma_f32_16x16x32_bf16 v[100:103], v[152:155], v[192:195], v[100:103]
	v_mfma_f32_16x16x32_bf16 v[92:95], v[144:147], v[200:203], v[92:95]
	v_mfma_f32_16x16x32_bf16 v[84:87], v[152:155], v[200:203], v[84:87]
	s_setprio 0
	s_setprio 1
	v_mfma_f32_16x16x32_bf16 v[112:115], v[156:159], v[172:175], v[112:115]
	v_mfma_f32_16x16x32_bf16 v[104:107], v[164:167], v[172:175], v[104:107]
	v_mfma_f32_16x16x32_bf16 v[96:99], v[156:159], v[180:183], v[96:99]
	v_mfma_f32_16x16x32_bf16 v[88:91], v[164:167], v[180:183], v[88:91]
	v_mfma_f32_16x16x32_bf16 v[80:83], v[156:159], v[188:191], v[80:83]
	v_mfma_f32_16x16x32_bf16 v[76:79], v[164:167], v[188:191], v[76:79]
	v_mfma_f32_16x16x32_bf16 v[72:75], v[156:159], v[196:199], v[72:75]
	v_mfma_f32_16x16x32_bf16 v[68:71], v[164:167], v[196:199], v[68:71]
	v_mfma_f32_16x16x32_bf16 v[112:115], v[160:163], v[176:179], v[112:115]
	v_mfma_f32_16x16x32_bf16 v[104:107], v[168:171], v[176:179], v[104:107]
	v_mfma_f32_16x16x32_bf16 v[96:99], v[160:163], v[184:187], v[96:99]
	v_mfma_f32_16x16x32_bf16 v[88:91], v[168:171], v[184:187], v[88:91]
	v_mfma_f32_16x16x32_bf16 v[80:83], v[160:163], v[192:195], v[80:83]
	v_mfma_f32_16x16x32_bf16 v[76:79], v[168:171], v[192:195], v[76:79]
	v_mfma_f32_16x16x32_bf16 v[72:75], v[160:163], v[200:203], v[72:75]
	v_mfma_f32_16x16x32_bf16 v[68:71], v[168:171], v[200:203], v[68:71]
	s_setprio 0
	s_barrier
	s_sleep 2
	s_add_i32 s24, s48, s0
	v_lshl_add_u64 v[204:205], v[204:205], 0, s[66:67]
	s_mov_b32 m0, s24
	ds_read_b128 v[172:175], v139 offset:49152
	ds_read_b128 v[176:179], v139 offset:50176
	ds_read_b128 v[180:183], v139 offset:51200
	ds_read_b128 v[184:187], v139 offset:52224
	ds_read_b128 v[188:191], v139 offset:53248
	ds_read_b128 v[192:195], v139 offset:54272
	ds_read_b128 v[196:199], v139 offset:55296
	ds_read_b128 v[200:203], v139 offset:56320
	global_load_lds_dwordx4 v[204:205], off
	s_add_i32 m0, s24, 0x2000
	s_add_u32 s22, s22, 0x80080
	v_lshl_add_u64 v[204:205], v[206:207], 0, s[66:67]
	s_addc_u32 s23, s23, 0
	s_add_i32 s24, s49, s0
	global_load_lds_dwordx4 v[204:205], off
	v_lshl_add_u64 v[204:205], s[22:23], 0, v[2:3]
	s_mov_b32 m0, s24
	s_nop 0
	global_load_lds_dwordx4 v[204:205], off
	v_lshl_add_u64 v[204:205], s[22:23], 0, v[0:1]
	s_add_i32 m0, s24, 0x2000
	s_nop 0
	global_load_lds_dwordx4 v[204:205], off
	v_lshl_add_u64 v[204:205], v[208:209], 0, s[66:67]
	s_mov_b32 m0, s1
	s_nop 0
	global_load_lds_dwordx4 v[204:205], off
	v_lshl_add_u64 v[204:205], v[210:211], 0, s[66:67]
	s_mov_b32 m0, s34
	s_nop 0
	global_load_lds_dwordx4 v[204:205], off
	s_waitcnt vmcnt(8)
	s_waitcnt lgkmcnt(0)
	s_barrier
	s_setprio 1
	s_waitcnt lgkmcnt(0)
	v_mfma_f32_16x16x32_bf16 v[64:67], v[140:143], v[172:175], v[64:67]
	v_mfma_f32_16x16x32_bf16 v[60:63], v[148:151], v[172:175], v[60:63]
	v_mfma_f32_16x16x32_bf16 v[56:59], v[140:143], v[180:183], v[56:59]
	v_mfma_f32_16x16x32_bf16 v[52:55], v[148:151], v[180:183], v[52:55]
	v_mfma_f32_16x16x32_bf16 v[40:43], v[140:143], v[188:191], v[40:43]
	v_mfma_f32_16x16x32_bf16 v[36:39], v[148:151], v[188:191], v[36:39]
	v_mfma_f32_16x16x32_bf16 v[24:27], v[140:143], v[196:199], v[24:27]
	v_mfma_f32_16x16x32_bf16 v[20:23], v[148:151], v[196:199], v[20:23]
	v_mfma_f32_16x16x32_bf16 v[64:67], v[144:147], v[176:179], v[64:67]
	v_mfma_f32_16x16x32_bf16 v[60:63], v[152:155], v[176:179], v[60:63]
	v_mfma_f32_16x16x32_bf16 v[56:59], v[144:147], v[184:187], v[56:59]
	v_mfma_f32_16x16x32_bf16 v[52:55], v[152:155], v[184:187], v[52:55]
	v_mfma_f32_16x16x32_bf16 v[40:43], v[144:147], v[192:195], v[40:43]
	v_mfma_f32_16x16x32_bf16 v[36:39], v[152:155], v[192:195], v[36:39]
	v_mfma_f32_16x16x32_bf16 v[24:27], v[144:147], v[200:203], v[24:27]
	v_mfma_f32_16x16x32_bf16 v[20:23], v[152:155], v[200:203], v[20:23]
	s_setprio 0
	s_setprio 1
	v_mfma_f32_16x16x32_bf16 v[48:51], v[156:159], v[172:175], v[48:51]
	v_mfma_f32_16x16x32_bf16 v[44:47], v[164:167], v[172:175], v[44:47]
	v_mfma_f32_16x16x32_bf16 v[32:35], v[156:159], v[180:183], v[32:35]
	v_mfma_f32_16x16x32_bf16 v[28:31], v[164:167], v[180:183], v[28:31]
	v_mfma_f32_16x16x32_bf16 v[16:19], v[156:159], v[188:191], v[16:19]
	v_mfma_f32_16x16x32_bf16 v[12:15], v[164:167], v[188:191], v[12:15]
	v_mfma_f32_16x16x32_bf16 v[8:11], v[156:159], v[196:199], v[8:11]
	v_mfma_f32_16x16x32_bf16 v[4:7], v[164:167], v[196:199], v[4:7]
	v_mfma_f32_16x16x32_bf16 v[48:51], v[160:163], v[176:179], v[48:51]
	v_mfma_f32_16x16x32_bf16 v[44:47], v[168:171], v[176:179], v[44:47]
	v_mfma_f32_16x16x32_bf16 v[32:35], v[160:163], v[184:187], v[32:35]
	v_mfma_f32_16x16x32_bf16 v[28:31], v[168:171], v[184:187], v[28:31]
	v_mfma_f32_16x16x32_bf16 v[16:19], v[160:163], v[192:195], v[16:19]
	v_mfma_f32_16x16x32_bf16 v[12:15], v[168:171], v[192:195], v[12:15]
	v_mfma_f32_16x16x32_bf16 v[8:11], v[160:163], v[200:203], v[8:11]
	v_mfma_f32_16x16x32_bf16 v[4:7], v[168:171], v[200:203], v[4:7]
	s_setprio 0
	s_barrier
	s_add_i32 s47, s47, 2
	s_add_u32 s20, s20, 0x100
	s_addc_u32 s21, s21, 0
	s_add_u32 s45, s45, 0x100
	s_addc_u32 s46, s46, 0
	s_cmp_gt_u32 s47, 29
	s_cbranch_scc0 .LBB0_495
	s_and_b64 vcc, exec, s[8:9]
	s_cbranch_vccz .LBB0_498
	s_barrier

.LBB0_1010:
	s_sleep 2
	s_add_u32 s24, s22, 0xfff80080
	s_addc_u32 s25, s23, -1
	s_add_i32 s49, 0, 0x10000
	s_cmp_eq_u32 s48, 28
	s_cselect_b32 s27, s13, s25
	s_cselect_b32 s26, s19, s24
	s_cselect_b32 s25, s11, s47
	s_cselect_b32 s24, s45, s46
	s_add_i32 s52, 0, 0x14000
	v_add_u32_e32 v144, s49, v219
	v_add_u32_e32 v160, s52, v219
	ds_read_b128 v[116:119], v144
	ds_read_b128 v[124:127], v144 offset:1024
	ds_read_b128 v[132:135], v144 offset:2048
	ds_read_b128 v[144:147], v144 offset:3072
	ds_read_b128 v[148:151], v160
	ds_read_b128 v[152:155], v160 offset:1024
	ds_read_b128 v[156:159], v160 offset:2048
	ds_read_b128 v[160:163], v160 offset:3072
	v_lshl_add_u64 v[204:205], s[22:23], 0, v[192:193]
	s_add_i32 m0, s21, 0xc000
	ds_read_b128 v[164:167], v221
	ds_read_b128 v[168:171], v221 offset:1024
	ds_read_b128 v[172:175], v221 offset:2048
	ds_read_b128 v[176:179], v221 offset:3072
	ds_read_b128 v[180:183], v221 offset:4096
	ds_read_b128 v[184:187], v221 offset:5120
	ds_read_b128 v[196:199], v221 offset:6144
	ds_read_b128 v[200:203], v221 offset:7168
	global_load_lds_dwordx4 v[204:205], off
	v_lshl_add_u64 v[204:205], s[22:23], 0, v[194:195]
	s_add_i32 m0, s21, 0xe000
	s_nop 0
	global_load_lds_dwordx4 v[204:205], off
	s_waitcnt vmcnt(8)
	s_waitcnt lgkmcnt(0)
	s_barrier
	s_setprio 1
	s_waitcnt lgkmcnt(0)
	v_mfma_f32_16x16x32_bf16 v[140:143], v[116:119], v[164:167], v[140:143]
	v_mfma_f32_16x16x32_bf16 v[136:139], v[132:135], v[164:167], v[136:139]
	v_mfma_f32_16x16x32_bf16 v[112:115], v[116:119], v[172:175], v[112:115]
	v_mfma_f32_16x16x32_bf16 v[108:111], v[132:135], v[172:175], v[108:111]
	v_mfma_f32_16x16x32_bf16 v[96:99], v[116:119], v[180:183], v[96:99]
	v_mfma_f32_16x16x32_bf16 v[92:95], v[132:135], v[180:183], v[92:95]
	v_mfma_f32_16x16x32_bf16 v[80:83], v[116:119], v[196:199], v[80:83]
	v_mfma_f32_16x16x32_bf16 v[76:79], v[132:135], v[196:199], v[76:79]
	v_mfma_f32_16x16x32_bf16 v[140:143], v[124:127], v[168:171], v[140:143]
	v_mfma_f32_16x16x32_bf16 v[136:139], v[144:147], v[168:171], v[136:139]
	v_mfma_f32_16x16x32_bf16 v[112:115], v[124:127], v[176:179], v[112:115]
	v_mfma_f32_16x16x32_bf16 v[108:111], v[144:147], v[176:179], v[108:111]
	v_mfma_f32_16x16x32_bf16 v[96:99], v[124:127], v[184:187], v[96:99]
	v_mfma_f32_16x16x32_bf16 v[92:95], v[144:147], v[184:187], v[92:95]
	v_mfma_f32_16x16x32_bf16 v[80:83], v[124:127], v[200:203], v[80:83]
	v_mfma_f32_16x16x32_bf16 v[76:79], v[144:147], v[200:203], v[76:79]
	s_setprio 0
	s_setprio 1
	v_mfma_f32_16x16x32_bf16 v[128:131], v[148:151], v[164:167], v[128:131]
	v_mfma_f32_16x16x32_bf16 v[120:123], v[156:159], v[164:167], v[120:123]
	v_mfma_f32_16x16x32_bf16 v[104:107], v[148:151], v[172:175], v[104:107]
	v_mfma_f32_16x16x32_bf16 v[100:103], v[156:159], v[172:175], v[100:103]
	v_mfma_f32_16x16x32_bf16 v[88:91], v[148:151], v[180:183], v[88:91]
	v_mfma_f32_16x16x32_bf16 v[84:87], v[156:159], v[180:183], v[84:87]
	v_mfma_f32_16x16x32_bf16 v[72:75], v[148:151], v[196:199], v[72:75]
	v_mfma_f32_16x16x32_bf16 v[68:71], v[156:159], v[196:199], v[68:71]
	v_mfma_f32_16x16x32_bf16 v[128:131], v[152:155], v[168:171], v[128:131]
	v_mfma_f32_16x16x32_bf16 v[120:123], v[160:163], v[168:171], v[120:123]
	v_mfma_f32_16x16x32_bf16 v[104:107], v[152:155], v[176:179], v[104:107]
	v_mfma_f32_16x16x32_bf16 v[100:103], v[160:163], v[176:179], v[100:103]
	v_mfma_f32_16x16x32_bf16 v[88:91], v[152:155], v[184:187], v[88:91]
	v_mfma_f32_16x16x32_bf16 v[84:87], v[160:163], v[184:187], v[84:87]
	v_mfma_f32_16x16x32_bf16 v[72:75], v[152:155], v[200:203], v[72:75]
	v_mfma_f32_16x16x32_bf16 v[68:71], v[160:163], v[200:203], v[68:71]
	s_setprio 0
	s_barrier
	s_sleep 2
	s_add_i32 s49, s49, s30
	v_lshl_add_u64 v[204:205], s[24:25], 0, v[2:3]
	s_mov_b32 m0, s49
	ds_read_b128 v[164:167], v221 offset:16384
	ds_read_b128 v[168:171], v221 offset:17408
	ds_read_b128 v[172:175], v221 offset:18432
	ds_read_b128 v[176:179], v221 offset:19456
	ds_read_b128 v[180:183], v221 offset:20480
	ds_read_b128 v[184:187], v221 offset:21504
	ds_read_b128 v[196:199], v221 offset:22528
	ds_read_b128 v[200:203], v221 offset:23552
	global_load_lds_dwordx4 v[204:205], off
	s_add_i32 m0, s49, 0x2000
	s_add_u32 s50, s24, 0x80000
	v_lshl_add_u64 v[206:207], s[24:25], 0, v[190:191]
	s_addc_u32 s51, s25, 0
	s_add_i32 s49, s52, s30
	global_load_lds_dwordx4 v[206:207], off
	v_lshl_add_u64 v[208:209], s[50:51], 0, v[2:3]
	s_mov_b32 m0, s49
	v_lshl_add_u64 v[210:211], s[26:27], 0, v[188:189]
	global_load_lds_dwordx4 v[208:209], off
	v_lshl_add_u64 v[208:209], s[50:51], 0, v[190:191]
	s_add_i32 m0, s49, 0x2000
	s_nop 0
	global_load_lds_dwordx4 v[208:209], off
	v_lshl_add_u64 v[208:209], s[26:27], 0, v[0:1]
	s_mov_b32 m0, s21
	s_nop 0
	global_load_lds_dwordx4 v[208:209], off
	s_mov_b32 m0, s31
	s_nop 0
	global_load_lds_dwordx4 v[210:211], off
	s_waitcnt vmcnt(8)
	s_waitcnt lgkmcnt(0)
	s_barrier
	s_setprio 1
	s_waitcnt lgkmcnt(0)
	v_mfma_f32_16x16x32_bf16 v[64:67], v[116:119], v[164:167], v[64:67]
	v_mfma_f32_16x16x32_bf16 v[60:63], v[132:135], v[164:167], v[60:63]
	v_mfma_f32_16x16x32_bf16 v[48:51], v[116:119], v[172:175], v[48:51]
	v_mfma_f32_16x16x32_bf16 v[44:47], v[132:135], v[172:175], v[44:47]
	v_mfma_f32_16x16x32_bf16 v[32:35], v[116:119], v[180:183], v[32:35]
	v_mfma_f32_16x16x32_bf16 v[28:31], v[132:135], v[180:183], v[28:31]
	v_mfma_f32_16x16x32_bf16 v[16:19], v[116:119], v[196:199], v[16:19]
	v_mfma_f32_16x16x32_bf16 v[12:15], v[132:135], v[196:199], v[12:15]
	v_mfma_f32_16x16x32_bf16 v[64:67], v[124:127], v[168:171], v[64:67]
	v_mfma_f32_16x16x32_bf16 v[60:63], v[144:147], v[168:171], v[60:63]
	v_mfma_f32_16x16x32_bf16 v[48:51], v[124:127], v[176:179], v[48:51]
	v_mfma_f32_16x16x32_bf16 v[44:47], v[144:147], v[176:179], v[44:47]
	v_mfma_f32_16x16x32_bf16 v[32:35], v[124:127], v[184:187], v[32:35]
	v_mfma_f32_16x16x32_bf16 v[28:31], v[144:147], v[184:187], v[28:31]
	v_mfma_f32_16x16x32_bf16 v[16:19], v[124:127], v[200:203], v[16:19]
	v_mfma_f32_16x16x32_bf16 v[12:15], v[144:147], v[200:203], v[12:15]
	s_setprio 0
	s_setprio 1
	v_mfma_f32_16x16x32_bf16 v[56:59], v[148:151], v[164:167], v[56:59]
	v_mfma_f32_16x16x32_bf16 v[52:55], v[156:159], v[164:167], v[52:55]
	v_mfma_f32_16x16x32_bf16 v[40:43], v[148:151], v[172:175], v[40:43]
	v_mfma_f32_16x16x32_bf16 v[36:39], v[156:159], v[172:175], v[36:39]
	v_mfma_f32_16x16x32_bf16 v[24:27], v[148:151], v[180:183], v[24:27]
	v_mfma_f32_16x16x32_bf16 v[20:23], v[156:159], v[180:183], v[20:23]
	v_mfma_f32_16x16x32_bf16 v[8:11], v[148:151], v[196:199], v[8:11]
	v_mfma_f32_16x16x32_bf16 v[4:7], v[156:159], v[196:199], v[4:7]
	v_mfma_f32_16x16x32_bf16 v[56:59], v[152:155], v[168:171], v[56:59]
	v_mfma_f32_16x16x32_bf16 v[52:55], v[160:163], v[168:171], v[52:55]
	v_mfma_f32_16x16x32_bf16 v[40:43], v[152:155], v[176:179], v[40:43]
	v_mfma_f32_16x16x32_bf16 v[36:39], v[160:163], v[176:179], v[36:39]
	v_mfma_f32_16x16x32_bf16 v[24:27], v[152:155], v[184:187], v[24:27]
	v_mfma_f32_16x16x32_bf16 v[20:23], v[160:163], v[184:187], v[20:23]
	v_mfma_f32_16x16x32_bf16 v[8:11], v[152:155], v[200:203], v[8:11]
	v_mfma_f32_16x16x32_bf16 v[4:7], v[160:163], v[200:203], v[4:7]
	s_setprio 0
	s_barrier
	s_sleep 2
	s_add_i32 s49, 0, 0x18000
	s_add_i32 s50, 0, 0x1c000
	v_add_u32_e32 v144, s49, v219
	v_add_u32_e32 v160, s50, v219
	ds_read_b128 v[116:119], v144
	ds_read_b128 v[124:127], v144 offset:1024
	ds_read_b128 v[132:135], v144 offset:2048
	ds_read_b128 v[144:147], v144 offset:3072
	ds_read_b128 v[148:151], v160
	ds_read_b128 v[152:155], v160 offset:1024
	ds_read_b128 v[156:159], v160 offset:2048
	ds_read_b128 v[160:163], v160 offset:3072
	s_add_u32 s26, s26, 0x80000
	s_addc_u32 s27, s27, 0
	s_mov_b32 m0, s35
	v_lshl_add_u64 v[212:213], s[26:27], 0, v[0:1]
	ds_read_b128 v[164:167], v221 offset:32768
	ds_read_b128 v[168:171], v221 offset:33792
	ds_read_b128 v[172:175], v221 offset:34816
	ds_read_b128 v[176:179], v221 offset:35840
	ds_read_b128 v[180:183], v221 offset:36864
	ds_read_b128 v[184:187], v221 offset:37888
	ds_read_b128 v[196:199], v221 offset:38912
	ds_read_b128 v[200:203], v221 offset:39936
	global_load_lds_dwordx4 v[212:213], off
	v_lshl_add_u64 v[212:213], s[26:27], 0, v[188:189]
	s_mov_b32 m0, s40
	s_nop 0
	global_load_lds_dwordx4 v[212:213], off
	s_waitcnt vmcnt(8)
	s_waitcnt lgkmcnt(0)
	s_barrier
	s_setprio 1
	s_waitcnt lgkmcnt(0)
	v_mfma_f32_16x16x32_bf16 v[140:143], v[116:119], v[164:167], v[140:143]
	v_mfma_f32_16x16x32_bf16 v[136:139], v[132:135], v[164:167], v[136:139]
	v_mfma_f32_16x16x32_bf16 v[112:115], v[116:119], v[172:175], v[112:115]
	v_mfma_f32_16x16x32_bf16 v[108:111], v[132:135], v[172:175], v[108:111]
	v_mfma_f32_16x16x32_bf16 v[96:99], v[116:119], v[180:183], v[96:99]
	v_mfma_f32_16x16x32_bf16 v[92:95], v[132:135], v[180:183], v[92:95]
	v_mfma_f32_16x16x32_bf16 v[80:83], v[116:119], v[196:199], v[80:83]
	v_mfma_f32_16x16x32_bf16 v[76:79], v[132:135], v[196:199], v[76:79]
	v_mfma_f32_16x16x32_bf16 v[140:143], v[124:127], v[168:171], v[140:143]
	v_mfma_f32_16x16x32_bf16 v[136:139], v[144:147], v[168:171], v[136:139]
	v_mfma_f32_16x16x32_bf16 v[112:115], v[124:127], v[176:179], v[112:115]
	v_mfma_f32_16x16x32_bf16 v[108:111], v[144:147], v[176:179], v[108:111]
	v_mfma_f32_16x16x32_bf16 v[96:99], v[124:127], v[184:187], v[96:99]
	v_mfma_f32_16x16x32_bf16 v[92:95], v[144:147], v[184:187], v[92:95]
	v_mfma_f32_16x16x32_bf16 v[80:83], v[124:127], v[200:203], v[80:83]
	v_mfma_f32_16x16x32_bf16 v[76:79], v[144:147], v[200:203], v[76:79]
	s_setprio 0
	s_setprio 1
	v_mfma_f32_16x16x32_bf16 v[128:131], v[148:151], v[164:167], v[128:131]
	v_mfma_f32_16x16x32_bf16 v[120:123], v[156:159], v[164:167], v[120:123]
	v_mfma_f32_16x16x32_bf16 v[104:107], v[148:151], v[172:175], v[104:107]
	v_mfma_f32_16x16x32_bf16 v[100:103], v[156:159], v[172:175], v[100:103]
	v_mfma_f32_16x16x32_bf16 v[88:91], v[148:151], v[180:183], v[88:91]
	v_mfma_f32_16x16x32_bf16 v[84:87], v[156:159], v[180:183], v[84:87]
	v_mfma_f32_16x16x32_bf16 v[72:75], v[148:151], v[196:199], v[72:75]
	v_mfma_f32_16x16x32_bf16 v[68:71], v[156:159], v[196:199], v[68:71]
	v_mfma_f32_16x16x32_bf16 v[128:131], v[152:155], v[168:171], v[128:131]
	v_mfma_f32_16x16x32_bf16 v[120:123], v[160:163], v[168:171], v[120:123]
	v_mfma_f32_16x16x32_bf16 v[104:107], v[152:155], v[176:179], v[104:107]
	v_mfma_f32_16x16x32_bf16 v[100:103], v[160:163], v[176:179], v[100:103]
	v_mfma_f32_16x16x32_bf16 v[88:91], v[152:155], v[184:187], v[88:91]
	v_mfma_f32_16x16x32_bf16 v[84:87], v[160:163], v[184:187], v[84:87]
	v_mfma_f32_16x16x32_bf16 v[72:75], v[152:155], v[200:203], v[72:75]
	v_mfma_f32_16x16x32_bf16 v[68:71], v[160:163], v[200:203], v[68:71]
	s_setprio 0
	s_barrier
	s_sleep 2
	s_add_i32 s26, s49, s30
	v_lshl_add_u64 v[204:205], v[204:205], 0, s[66:67]
	s_mov_b32 m0, s26
	ds_read_b128 v[164:167], v221 offset:49152
	ds_read_b128 v[168:171], v221 offset:50176
	ds_read_b128 v[172:175], v221 offset:51200
	ds_read_b128 v[176:179], v221 offset:52224
	ds_read_b128 v[180:183], v221 offset:53248
	ds_read_b128 v[184:187], v221 offset:54272
	ds_read_b128 v[196:199], v221 offset:55296
	ds_read_b128 v[200:203], v221 offset:56320
	global_load_lds_dwordx4 v[204:205], off
	s_add_i32 m0, s26, 0x2000
	s_add_u32 s24, s24, 0x80080
	v_lshl_add_u64 v[204:205], v[206:207], 0, s[66:67]
	s_addc_u32 s25, s25, 0
	s_add_i32 s26, s50, s30
	global_load_lds_dwordx4 v[204:205], off
	v_lshl_add_u64 v[204:205], s[24:25], 0, v[2:3]
	s_mov_b32 m0, s26
	s_nop 0
	global_load_lds_dwordx4 v[204:205], off
	v_lshl_add_u64 v[204:205], s[24:25], 0, v[190:191]
	s_add_i32 m0, s26, 0x2000
	s_nop 0
	global_load_lds_dwordx4 v[204:205], off
	v_lshl_add_u64 v[204:205], v[208:209], 0, s[66:67]
	s_mov_b32 m0, s41
	s_nop 0
	global_load_lds_dwordx4 v[204:205], off
	v_lshl_add_u64 v[204:205], v[210:211], 0, s[66:67]
	s_mov_b32 m0, s42
	s_nop 0
	global_load_lds_dwordx4 v[204:205], off
	s_waitcnt vmcnt(8)
	s_waitcnt lgkmcnt(0)
	s_barrier
	s_setprio 1
	s_waitcnt lgkmcnt(0)
	v_mfma_f32_16x16x32_bf16 v[64:67], v[116:119], v[164:167], v[64:67]
	v_mfma_f32_16x16x32_bf16 v[60:63], v[132:135], v[164:167], v[60:63]
	v_mfma_f32_16x16x32_bf16 v[48:51], v[116:119], v[172:175], v[48:51]
	v_mfma_f32_16x16x32_bf16 v[44:47], v[132:135], v[172:175], v[44:47]
	v_mfma_f32_16x16x32_bf16 v[32:35], v[116:119], v[180:183], v[32:35]
	v_mfma_f32_16x16x32_bf16 v[28:31], v[132:135], v[180:183], v[28:31]
	v_mfma_f32_16x16x32_bf16 v[16:19], v[116:119], v[196:199], v[16:19]
	v_mfma_f32_16x16x32_bf16 v[12:15], v[132:135], v[196:199], v[12:15]
	v_mfma_f32_16x16x32_bf16 v[64:67], v[124:127], v[168:171], v[64:67]
	v_mfma_f32_16x16x32_bf16 v[60:63], v[144:147], v[168:171], v[60:63]
	v_mfma_f32_16x16x32_bf16 v[48:51], v[124:127], v[176:179], v[48:51]
	v_mfma_f32_16x16x32_bf16 v[44:47], v[144:147], v[176:179], v[44:47]
	v_mfma_f32_16x16x32_bf16 v[32:35], v[124:127], v[184:187], v[32:35]
	v_mfma_f32_16x16x32_bf16 v[28:31], v[144:147], v[184:187], v[28:31]
	v_mfma_f32_16x16x32_bf16 v[16:19], v[124:127], v[200:203], v[16:19]
	v_mfma_f32_16x16x32_bf16 v[12:15], v[144:147], v[200:203], v[12:15]
	s_setprio 0
	s_setprio 1
	v_mfma_f32_16x16x32_bf16 v[56:59], v[148:151], v[164:167], v[56:59]
	v_mfma_f32_16x16x32_bf16 v[52:55], v[156:159], v[164:167], v[52:55]
	v_mfma_f32_16x16x32_bf16 v[40:43], v[148:151], v[172:175], v[40:43]
	v_mfma_f32_16x16x32_bf16 v[36:39], v[156:159], v[172:175], v[36:39]
	v_mfma_f32_16x16x32_bf16 v[24:27], v[148:151], v[180:183], v[24:27]
	v_mfma_f32_16x16x32_bf16 v[20:23], v[156:159], v[180:183], v[20:23]
	v_mfma_f32_16x16x32_bf16 v[8:11], v[148:151], v[196:199], v[8:11]
	v_mfma_f32_16x16x32_bf16 v[4:7], v[156:159], v[196:199], v[4:7]
	v_mfma_f32_16x16x32_bf16 v[56:59], v[152:155], v[168:171], v[56:59]
	v_mfma_f32_16x16x32_bf16 v[52:55], v[160:163], v[168:171], v[52:55]
	v_mfma_f32_16x16x32_bf16 v[40:43], v[152:155], v[176:179], v[40:43]
	v_mfma_f32_16x16x32_bf16 v[36:39], v[160:163], v[176:179], v[36:39]
	v_mfma_f32_16x16x32_bf16 v[24:27], v[152:155], v[184:187], v[24:27]
	v_mfma_f32_16x16x32_bf16 v[20:23], v[160:163], v[184:187], v[20:23]
	v_mfma_f32_16x16x32_bf16 v[8:11], v[152:155], v[200:203], v[8:11]
	v_mfma_f32_16x16x32_bf16 v[4:7], v[160:163], v[200:203], v[4:7]
	s_setprio 0
	s_barrier
	s_add_i32 s48, s48, 2
	s_add_u32 s22, s22, 0x100
	s_addc_u32 s23, s23, 0
	s_add_u32 s46, s46, 0x100
	s_addc_u32 s47, s47, 0
	s_cmp_gt_u32 s48, 29
	s_cbranch_scc0 .LBB0_1010
	s_and_b64 vcc, exec, s[8:9]
	s_cbranch_vccz .LBB0_1013
	s_barrier
